# scan tile rewritten by hand: 5 wide loads per producer wave and packed f32 math, consumer 31 VALU per step, 1-step LDS prefetch
# speedup vs baseline: 1.0131x; 1.0131x over previous
; DEV int ltid() { int t = threadIdx.x; asm volatile("" : "+v"(t)); return t; }
; DEV float bf2f(bf16_t h) { return __uint_as_float(((unsigned)h) << 16); }
; DEV void scan_tile(const Params& p, int l, int tile, char* smem) {
;   const int half = tile & 1, dir = (tile >> 1) & 1, h = (tile >> 2) & 7, b = tile >> 5;
;   float* arr = (float*)smem;
;   float* ybuf = arr + 2 * 32 * 384;
;   const bf16_t* ZRS = (const bf16_t*)(p.ws + O_ZRS);
;   const bf16_t* E = (const bf16_t*)(p.ws + (dir ? O_EB : O_EF));
;   const bf16_t* Aa = (const bf16_t*)(p.ws + (dir ? O_AB : O_AF));
;   bf16_t* YS = (bf16_t*)(p.ws + (dir ? O_YSB : O_YSF));
;   const int tid = ltid(), lane = tid & 63;
;   const int w = __builtin_amdgcn_readfirstlane(tid >> 6);
;   const int col = h * 64 + lane;
;   const float kkp = p.rwkv_kk[l * 512 + col], kap = p.rwkv_ka[l * 512 + col];
;   auto produce = [&](int ch, int buf, int pw, int npw) {
; #pragma unroll
;     for (int i0 = 0; i0 < 32; i0 += 4 * npw) {
;       bf16_t rr[4], rk[4], rv[4], re[4], ra[4];
; #pragma unroll
;       for (int i = 0; i < 4; ++i) {
;         const int R = scan_row(ch * 32 + i0 + pw + npw * i, dir, b);
;         rr[i] = ZRS[(size_t)R * 1536 + col];
;         rk[i] = ZRS[(size_t)R * 1536 + 512 + col];
;         rv[i] = ZRS[(size_t)R * 1536 + 1024 + col];
;         re[i] = E[(size_t)R * 512 + col];
;         ra[i] = Aa[(size_t)R * 512 + col];
;       }
; #pragma unroll
;       for (int i = 0; i < 4; ++i) {
;         const int sl = i0 + pw + npw * i;
;         const float r = bf2f(rr[i]), k = bf2f(rk[i]), v = bf2f(rv[i]), e = bf2f(re[i]), a = bf2f(ra[i]);
;         const float kkv = k * kkp;
;         const float inv = __builtin_amdgcn_rsqf(fmaxf(wsum(kkv * kkv), 1e-24f));
;         const float kk = kkv * inv;
;         float* d = arr + (buf * 32 + sl) * 384 + lane;
;         d[0] = -kk;
;         d[64] = __expf(-e);
;         d[128] = kk * a;
;         d[192] = k * (1.f + (a - 1.f) * kap);
;         d[256] = r;
;         d[320] = v;
;       }
;     }
;   };
.LBB0_193:
	s_and_b32 s30, s94, 1
	s_bfe_u32 s31, s94, 0x10001
	s_bfe_u32 s36, s94, 0x30002
	s_lshr_b32 s37, s94, 5
	v_readfirstlane_b32 s47, v226
	s_lshl_b32 s58, s36, 7
	s_add_u32 s38, s74, 0xee00000
	s_addc_u32 s39, s75, 0
	s_add_u32 s38, s38, s58
	s_addc_u32 s39, s39, 0
	s_lshr_b32 s47, s47, 6
	s_cmp_eq_u32 s31, 0
	s_cselect_b32 s59, 0, 0x6600000
	s_add_u32 s40, s74, s59
	s_addc_u32 s41, s75, 0
	s_add_u32 s40, s40, s58
	s_addc_u32 s41, s41, 0
	s_mov_b32 s59, 0xaa00000
	s_cmp_eq_u32 s31, 0
	s_cselect_b32 s59, 0x8800000, s59
	s_add_u32 s42, s74, s59
	s_addc_u32 s43, s75, 0
	s_add_u32 s42, s42, s58
	s_addc_u32 s43, s43, 0
	s_mov_b32 s59, 0x15400000
	s_cmp_eq_u32 s31, 0
	s_cselect_b32 s59, 0xcc00000, s59
	s_add_u32 s44, s74, s59
	s_addc_u32 s45, s75, 0
	s_lshl_b32 s59, s30, 6
	s_add_u32 s58, s58, s59
	s_add_u32 s44, s44, s58
	s_addc_u32 s45, s45, 0
	s_mov_b32 s46, 0
	v_and_b32_e32 v120, 63, v226
	v_and_b32_e32 v121, 7, v120
	v_lshrrev_b32_e32 v122, 3, v120
	s_cmp_lt_u32 s47, 4
	s_cbranch_scc1 .Lsc_consumer
	s_sub_u32 s58, s47, 4
	s_lshl_b32 s58, s58, 3
	v_add_u32_e32 v123, s58, v122
	v_sub_u32_e32 v32, 31, v123
	s_cmp_eq_u32 s31, 0
	s_cselect_b64 vcc, -1, 0
	v_cndmask_b32_e32 v32, v32, v123, vcc
	v_lshlrev_b32_e32 v33, 4, v121
	v_mul_u32_u24_e32 v20, 0xc00, v32
	v_add_u32_e32 v20, v20, v33
	v_lshl_add_u32 v21, v32, 10, v33
	v_mul_u32_u24_e32 v22, 0x600, v123
	v_lshl_add_u32 v22, v121, 5, v22
	v_lshlrev_b32_e32 v23, 7, v123
	v_lshl_add_u32 v23, v121, 4, v23
	v_add_u32_e32 v23, 0x18000, v23
	v_lshlrev_b32_e32 v24, 10, v32
	v_lshl_add_u32 v24, v121, 3, v24
	s_lshl_b32 s58, s36, 6
	s_add_u32 s58, s58, s79
	v_lshl_add_u32 v34, v121, 3, s58
	v_lshlrev_b32_e32 v34, 2, v34
	global_load_dwordx4 v[40:43], v34, s[8:9]
	global_load_dwordx4 v[44:47], v34, s[8:9] offset:16
	global_load_dwordx4 v[48:51], v34, s[10:11]
	global_load_dwordx4 v[52:55], v34, s[10:11] offset:16
	v_mov_b32_e32 v98, 0xbfb8aa3b
	v_mov_b32_e32 v99, 0xbfb8aa3b
	v_mov_b32_e32 v124, -1.0
	v_mov_b32_e32 v125, -1.0
	v_mov_b32_e32 v126, 1.0
	v_mov_b32_e32 v127, 1.0
	s_mov_b32 s54, 0xc000
	s_sub_u32 s60, s46, 8
	s_cmp_lt_u32 s46, 8
	s_cselect_b32 s60, s46, s60
	s_lshl_b32 s60, s60, 5
	s_lshl_b32 s61, s37, 8
	s_add_u32 s61, s61, 0x8000
	s_lshl_b32 s59, s37, 12
	s_cmp_lt_u32 s46, 8
	s_cselect_b32 s59, s61, s59
	s_movk_i32 s61, 0xfe0
	s_cselect_b32 s61, 0xe0, s61
	s_sub_u32 s61, s61, s60
	s_cmp_eq_u32 s31, 0
	s_cselect_b32 s60, s60, s61
	s_add_u32 s59, s59, s60
	s_mul_i32 s60, s59, 0xc00
	s_add_u32 s48, s38, s60
	s_addc_u32 s49, s39, 0
	s_lshl_b32 s60, s59, 10
	s_add_u32 s50, s40, s60
	s_addc_u32 s51, s41, 0
	s_add_u32 s52, s42, s60
	s_addc_u32 s53, s43, 0
	global_load_dwordx4 v[0:3], v20, s[48:49]
	global_load_dwordx4 v[4:7], v20, s[48:49] offset:1024
	global_load_dwordx4 v[8:11], v20, s[48:49] offset:2048
	global_load_dwordx4 v[12:15], v21, s[50:51]
	global_load_dwordx4 v[16:19], v21, s[52:53]
	s_barrier
	s_waitcnt vmcnt(0)
	v_lshlrev_b32_e32 v56, 16, v4
	v_and_b32_e32 v57, 0xffff0000, v4
	v_lshlrev_b32_e32 v58, 16, v5
	v_and_b32_e32 v59, 0xffff0000, v5
	v_lshlrev_b32_e32 v60, 16, v6
	v_and_b32_e32 v61, 0xffff0000, v6
	v_lshlrev_b32_e32 v62, 16, v7
	v_and_b32_e32 v63, 0xffff0000, v7
	v_lshlrev_b32_e32 v64, 16, v16
	v_and_b32_e32 v65, 0xffff0000, v16
	v_lshlrev_b32_e32 v66, 16, v17
	v_and_b32_e32 v67, 0xffff0000, v17
	v_lshlrev_b32_e32 v68, 16, v18
	v_and_b32_e32 v69, 0xffff0000, v18
	v_lshlrev_b32_e32 v70, 16, v19
	v_and_b32_e32 v71, 0xffff0000, v19
	v_lshlrev_b32_e32 v72, 16, v12
	v_and_b32_e32 v73, 0xffff0000, v12
	v_lshlrev_b32_e32 v74, 16, v13
	v_and_b32_e32 v75, 0xffff0000, v13
	v_lshlrev_b32_e32 v76, 16, v14
	v_and_b32_e32 v77, 0xffff0000, v14
	v_lshlrev_b32_e32 v78, 16, v15
	v_and_b32_e32 v79, 0xffff0000, v15
	v_lshlrev_b32_e32 v80, 16, v0
	v_and_b32_e32 v81, 0xffff0000, v0
	v_lshlrev_b32_e32 v82, 16, v1
	v_and_b32_e32 v83, 0xffff0000, v1
	v_lshlrev_b32_e32 v84, 16, v2
	v_and_b32_e32 v85, 0xffff0000, v2
	v_lshlrev_b32_e32 v86, 16, v3
	v_and_b32_e32 v87, 0xffff0000, v3
	v_lshlrev_b32_e32 v88, 16, v8
	v_and_b32_e32 v89, 0xffff0000, v8
	v_lshlrev_b32_e32 v90, 16, v9
	v_and_b32_e32 v91, 0xffff0000, v9
	v_lshlrev_b32_e32 v92, 16, v10
	v_and_b32_e32 v93, 0xffff0000, v10
	v_lshlrev_b32_e32 v94, 16, v11
	v_and_b32_e32 v95, 0xffff0000, v11
	s_mov_b32 s76, 1
	s_sub_u32 s60, s76, 8
	s_cmp_lt_u32 s76, 8
	s_cselect_b32 s60, s76, s60
	s_lshl_b32 s60, s60, 5
	s_lshl_b32 s61, s37, 8
	s_add_u32 s61, s61, 0x8000
	s_lshl_b32 s59, s37, 12
	s_cmp_lt_u32 s76, 8
	s_cselect_b32 s59, s61, s59
	s_movk_i32 s61, 0xfe0
	s_cselect_b32 s61, 0xe0, s61
	s_sub_u32 s61, s61, s60
	s_cmp_eq_u32 s31, 0
	s_cselect_b32 s60, s60, s61
	s_add_u32 s59, s59, s60
	s_mul_i32 s60, s59, 0xc00
	s_add_u32 s48, s38, s60
	s_addc_u32 s49, s39, 0
	s_lshl_b32 s60, s59, 10
	s_add_u32 s50, s40, s60
	s_addc_u32 s51, s41, 0
	s_add_u32 s52, s42, s60
	s_addc_u32 s53, s43, 0
	global_load_dwordx4 v[0:3], v20, s[48:49]
	global_load_dwordx4 v[4:7], v20, s[48:49] offset:1024
	global_load_dwordx4 v[8:11], v20, s[48:49] offset:2048
	global_load_dwordx4 v[12:15], v21, s[50:51]
	global_load_dwordx4 v[16:19], v21, s[52:53]
	v_pk_mul_f32 v[100:101], v[56:57], v[40:41]
	v_pk_mul_f32 v[102:103], v[58:59], v[42:43]
	v_pk_mul_f32 v[104:105], v[60:61], v[44:45]
	v_pk_mul_f32 v[106:107], v[62:63], v[46:47]
	v_pk_mul_f32 v[72:73], v[72:73], v[98:99]
	v_pk_mul_f32 v[74:75], v[74:75], v[98:99]
	v_pk_mul_f32 v[76:77], v[76:77], v[98:99]
	v_pk_mul_f32 v[78:79], v[78:79], v[98:99]
	v_pk_mul_f32 v[32:33], v[100:101], v[100:101]
	v_pk_fma_f32 v[32:33], v[102:103], v[102:103], v[32:33]
	v_pk_fma_f32 v[32:33], v[104:105], v[104:105], v[32:33]
; DEV float bf2f(bf16_t h) { return __uint_as_float(((unsigned)h) << 16); }
; DEV void scan_tile(const Params& p, int l, int tile, char* smem) {
;     ...
;   auto produce = [&](int ch, int buf, int pw, int npw) {
; #pragma unroll
;     for (int i0 = 0; i0 < 32; i0 += 4 * npw) {
;       bf16_t rr[4], rk[4], rv[4], re[4], ra[4];
; #pragma unroll
;       for (int i = 0; i < 4; ++i) {
;         const int R = scan_row(ch * 32 + i0 + pw + npw * i, dir, b);
;         rr[i] = ZRS[(size_t)R * 1536 + col];
;         rk[i] = ZRS[(size_t)R * 1536 + 512 + col];
;         rv[i] = ZRS[(size_t)R * 1536 + 1024 + col];
;         re[i] = E[(size_t)R * 512 + col];
;         ra[i] = Aa[(size_t)R * 512 + col];
;       }
; #pragma unroll
;       for (int i = 0; i < 4; ++i) {
;         const int sl = i0 + pw + npw * i;
;         const float r = bf2f(rr[i]), k = bf2f(rk[i]), v = bf2f(rv[i]), e = bf2f(re[i]), a = bf2f(ra[i]);
;         const float kkv = k * kkp;
;         const float inv = __builtin_amdgcn_rsqf(fmaxf(wsum(kkv * kkv), 1e-24f));
;         const float kk = kkv * inv;
;         float* d = arr + (buf * 32 + sl) * 384 + lane;
;         d[0] = -kk;
;         d[64] = __expf(-e);
;         d[128] = kk * a;
;         d[192] = k * (1.f + (a - 1.f) * kap);
;         d[256] = r;
;         d[320] = v;
;       }
;     }
;     ...
;       const int pw = w - 4;
;       if (ch > 0) flush(ch - 1, buf ^ 1, tid - 256);
;       if (ch + 1 < 136) produce(ch + 1, buf ^ 1, pw, 4);
	v_pk_fma_f32 v[32:33], v[106:107], v[106:107], v[32:33]
	v_add_f32_e32 v25, v32, v33
	v_pk_add_f32 v[116:117], v[64:65], v[124:125]
	v_pk_add_f32 v[118:119], v[66:67], v[124:125]
	v_add_f32_dpp v25, v25, v25 quad_perm:[1,0,3,2] row_mask:0xf bank_mask:0xf bound_ctrl:1
	v_pk_add_f32 v[120:121], v[68:69], v[124:125]
	v_pk_add_f32 v[122:123], v[70:71], v[124:125]
	v_add_f32_dpp v25, v25, v25 quad_perm:[2,3,0,1] row_mask:0xf bank_mask:0xf bound_ctrl:1
	v_exp_f32_e32 v72, v72
	v_exp_f32_e32 v73, v73
	v_add_f32_dpp v25, v25, v25 row_half_mirror row_mask:0xf bank_mask:0xf bound_ctrl:1
	v_exp_f32_e32 v74, v74
	v_exp_f32_e32 v75, v75
	v_exp_f32_e32 v76, v76
	v_exp_f32_e32 v77, v77
	v_exp_f32_e32 v78, v78
	v_exp_f32_e32 v79, v79
	v_max_f32_e32 v25, 0x179abe15, v25
	v_rsq_f32_e32 v25, v25
	v_pk_fma_f32 v[116:117], v[48:49], v[116:117], v[126:127]
	v_pk_fma_f32 v[118:119], v[50:51], v[118:119], v[126:127]
	v_pk_fma_f32 v[120:121], v[52:53], v[120:121], v[126:127]
	v_pk_fma_f32 v[122:123], v[54:55], v[122:123], v[126:127]
	v_sub_f32_e32 v26, 0, v25
	v_pk_mul_f32 v[116:117], v[116:117], v[56:57]
	v_pk_mul_f32 v[118:119], v[118:119], v[58:59]
	v_pk_mul_f32 v[120:121], v[120:121], v[60:61]
	v_pk_mul_f32 v[122:123], v[122:123], v[62:63]
	ds_write_b128 v22, v[72:75] offset:256
	ds_write_b128 v22, v[76:79] offset:272
	ds_write_b128 v22, v[80:83] offset:1024
	ds_write_b128 v22, v[84:87] offset:1040
	v_pk_mul_f32 v[100:101], v[100:101], v[26:27] op_sel_hi:[1,0]
	v_pk_mul_f32 v[102:103], v[102:103], v[26:27] op_sel_hi:[1,0]
	v_pk_mul_f32 v[104:105], v[104:105], v[26:27] op_sel_hi:[1,0]
	v_pk_mul_f32 v[106:107], v[106:107], v[26:27] op_sel_hi:[1,0]
	ds_write_b128 v22, v[88:91] offset:1280
	ds_write_b128 v22, v[92:95] offset:1296
	ds_write_b128 v22, v[116:119] offset:768
	ds_write_b128 v22, v[120:123] offset:784
	v_pk_mul_f32 v[108:109], v[100:101], v[64:65] neg_lo:[1,0] neg_hi:[1,0]
	v_pk_mul_f32 v[110:111], v[102:103], v[66:67] neg_lo:[1,0] neg_hi:[1,0]
	v_pk_mul_f32 v[112:113], v[104:105], v[68:69] neg_lo:[1,0] neg_hi:[1,0]
	v_pk_mul_f32 v[114:115], v[106:107], v[70:71] neg_lo:[1,0] neg_hi:[1,0]
	ds_write_b128 v22, v[100:103]
	ds_write_b128 v22, v[104:107] offset:16
	ds_write_b128 v22, v[108:111] offset:512
	ds_write_b128 v22, v[112:115] offset:528
	v_add_u32_e32 v22, s54, v22
	s_sub_u32 s54, 0, s54
	s_waitcnt lgkmcnt(0)
	s_barrier
.Lsc_ploop:
	s_cmp_ge_u32 s46, 135
	s_cbranch_scc1 .Lsc_pskip
	s_waitcnt vmcnt(0)
	v_lshlrev_b32_e32 v56, 16, v4
	v_and_b32_e32 v57, 0xffff0000, v4
	v_lshlrev_b32_e32 v58, 16, v5
	v_and_b32_e32 v59, 0xffff0000, v5
	v_lshlrev_b32_e32 v60, 16, v6
	v_and_b32_e32 v61, 0xffff0000, v6
	v_lshlrev_b32_e32 v62, 16, v7
	v_and_b32_e32 v63, 0xffff0000, v7
	v_lshlrev_b32_e32 v64, 16, v16
	v_and_b32_e32 v65, 0xffff0000, v16
	v_lshlrev_b32_e32 v66, 16, v17
	v_and_b32_e32 v67, 0xffff0000, v17
	v_lshlrev_b32_e32 v68, 16, v18
	v_and_b32_e32 v69, 0xffff0000, v18
	v_lshlrev_b32_e32 v70, 16, v19
	v_and_b32_e32 v71, 0xffff0000, v19
	v_lshlrev_b32_e32 v72, 16, v12
	v_and_b32_e32 v73, 0xffff0000, v12
	v_lshlrev_b32_e32 v74, 16, v13
	v_and_b32_e32 v75, 0xffff0000, v13
	v_lshlrev_b32_e32 v76, 16, v14
	v_and_b32_e32 v77, 0xffff0000, v14
	v_lshlrev_b32_e32 v78, 16, v15
	v_and_b32_e32 v79, 0xffff0000, v15
	v_lshlrev_b32_e32 v80, 16, v0
	v_and_b32_e32 v81, 0xffff0000, v0
	v_lshlrev_b32_e32 v82, 16, v1
	v_and_b32_e32 v83, 0xffff0000, v1
	v_lshlrev_b32_e32 v84, 16, v2
	v_and_b32_e32 v85, 0xffff0000, v2
	v_lshlrev_b32_e32 v86, 16, v3
	v_and_b32_e32 v87, 0xffff0000, v3
	v_lshlrev_b32_e32 v88, 16, v8
	v_and_b32_e32 v89, 0xffff0000, v8
	v_lshlrev_b32_e32 v90, 16, v9
	v_and_b32_e32 v91, 0xffff0000, v9
	v_lshlrev_b32_e32 v92, 16, v10
	v_and_b32_e32 v93, 0xffff0000, v10
	v_lshlrev_b32_e32 v94, 16, v11
	v_and_b32_e32 v95, 0xffff0000, v11
	s_cmp_ge_u32 s46, 134
	s_cbranch_scc1 .Lsc_pnoload
	s_add_u32 s76, s46, 2
	s_sub_u32 s60, s76, 8
	s_cmp_lt_u32 s76, 8
	s_cselect_b32 s60, s76, s60
	s_lshl_b32 s60, s60, 5
	s_lshl_b32 s61, s37, 8
	s_add_u32 s61, s61, 0x8000
	s_lshl_b32 s59, s37, 12
	s_cmp_lt_u32 s76, 8
	s_cselect_b32 s59, s61, s59
	s_movk_i32 s61, 0xfe0
	s_cselect_b32 s61, 0xe0, s61
	s_sub_u32 s61, s61, s60
	s_cmp_eq_u32 s31, 0
	s_cselect_b32 s60, s60, s61
	s_add_u32 s59, s59, s60
	s_mul_i32 s60, s59, 0xc00
	s_add_u32 s48, s38, s60
	s_addc_u32 s49, s39, 0
	s_lshl_b32 s60, s59, 10
	s_add_u32 s50, s40, s60
	s_addc_u32 s51, s41, 0
	s_add_u32 s52, s42, s60
	s_addc_u32 s53, s43, 0
	global_load_dwordx4 v[0:3], v20, s[48:49]
	global_load_dwordx4 v[4:7], v20, s[48:49] offset:1024
	global_load_dwordx4 v[8:11], v20, s[48:49] offset:2048
	global_load_dwordx4 v[12:15], v21, s[50:51]
	global_load_dwordx4 v[16:19], v21, s[52:53]
; DEV float bf2f(bf16_t h) { return __uint_as_float(((unsigned)h) << 16); }
; DEV void scan_tile(const Params& p, int l, int tile, char* smem) {
;     ...
;   auto produce = [&](int ch, int buf, int pw, int npw) {
; #pragma unroll
;     for (int i0 = 0; i0 < 32; i0 += 4 * npw) {
;       bf16_t rr[4], rk[4], rv[4], re[4], ra[4];
; #pragma unroll
;       for (int i = 0; i < 4; ++i) {
;         const int R = scan_row(ch * 32 + i0 + pw + npw * i, dir, b);
;         rr[i] = ZRS[(size_t)R * 1536 + col];
;         rk[i] = ZRS[(size_t)R * 1536 + 512 + col];
;         rv[i] = ZRS[(size_t)R * 1536 + 1024 + col];
;         re[i] = E[(size_t)R * 512 + col];
;         ra[i] = Aa[(size_t)R * 512 + col];
;       }
; #pragma unroll
;       for (int i = 0; i < 4; ++i) {
;         const int sl = i0 + pw + npw * i;
;         const float r = bf2f(rr[i]), k = bf2f(rk[i]), v = bf2f(rv[i]), e = bf2f(re[i]), a = bf2f(ra[i]);
;         const float kkv = k * kkp;
;         const float inv = __builtin_amdgcn_rsqf(fmaxf(wsum(kkv * kkv), 1e-24f));
;         const float kk = kkv * inv;
;         float* d = arr + (buf * 32 + sl) * 384 + lane;
;         d[0] = -kk;
;         d[64] = __expf(-e);
;         d[128] = kk * a;
;         d[192] = k * (1.f + (a - 1.f) * kap);
;         d[256] = r;
;         d[320] = v;
;       }
;     }
;   };
;   auto flush = [&](int ch, int buf, int t256) {
; #pragma unroll
;     for (int q = 0; q < 2; ++q) {
;       const int idx = t256 + 256 * q, sl = idx >> 4, rp = (idx & 15) * 2;
;       const int R = scan_row(ch * 32 + sl, dir, b);
;       const float* yb = ybuf + buf * 1024 + sl * 32 + rp;
;       *(unsigned*)(YS + (size_t)R * 512 + h * 64 + half * 32 + rp) = pk2(yb[0], yb[1]);
;     }
;   };
;     ...
;       const int pw = w - 4;
;       if (ch > 0) flush(ch - 1, buf ^ 1, tid - 256);
;       if (ch + 1 < 136) produce(ch + 1, buf ^ 1, pw, 4);
;     }
;     __syncthreads();
;   }
;   if (w >= 4) flush(135, 1, tid - 256);
.Lsc_pnoload:
	v_pk_mul_f32 v[100:101], v[56:57], v[40:41]
	v_pk_mul_f32 v[102:103], v[58:59], v[42:43]
	v_pk_mul_f32 v[104:105], v[60:61], v[44:45]
	v_pk_mul_f32 v[106:107], v[62:63], v[46:47]
	v_pk_mul_f32 v[72:73], v[72:73], v[98:99]
	v_pk_mul_f32 v[74:75], v[74:75], v[98:99]
	v_pk_mul_f32 v[76:77], v[76:77], v[98:99]
	v_pk_mul_f32 v[78:79], v[78:79], v[98:99]
	v_pk_mul_f32 v[32:33], v[100:101], v[100:101]
	v_pk_fma_f32 v[32:33], v[102:103], v[102:103], v[32:33]
	v_pk_fma_f32 v[32:33], v[104:105], v[104:105], v[32:33]
	v_pk_fma_f32 v[32:33], v[106:107], v[106:107], v[32:33]
	v_add_f32_e32 v25, v32, v33
	v_pk_add_f32 v[116:117], v[64:65], v[124:125]
	v_pk_add_f32 v[118:119], v[66:67], v[124:125]
	v_add_f32_dpp v25, v25, v25 quad_perm:[1,0,3,2] row_mask:0xf bank_mask:0xf bound_ctrl:1
	v_pk_add_f32 v[120:121], v[68:69], v[124:125]
	v_pk_add_f32 v[122:123], v[70:71], v[124:125]
	v_add_f32_dpp v25, v25, v25 quad_perm:[2,3,0,1] row_mask:0xf bank_mask:0xf bound_ctrl:1
	v_exp_f32_e32 v72, v72
	v_exp_f32_e32 v73, v73
	v_add_f32_dpp v25, v25, v25 row_half_mirror row_mask:0xf bank_mask:0xf bound_ctrl:1
	v_exp_f32_e32 v74, v74
	v_exp_f32_e32 v75, v75
	v_exp_f32_e32 v76, v76
	v_exp_f32_e32 v77, v77
	v_exp_f32_e32 v78, v78
	v_exp_f32_e32 v79, v79
	v_max_f32_e32 v25, 0x179abe15, v25
	v_rsq_f32_e32 v25, v25
	v_pk_fma_f32 v[116:117], v[48:49], v[116:117], v[126:127]
	v_pk_fma_f32 v[118:119], v[50:51], v[118:119], v[126:127]
	v_pk_fma_f32 v[120:121], v[52:53], v[120:121], v[126:127]
	v_pk_fma_f32 v[122:123], v[54:55], v[122:123], v[126:127]
	v_sub_f32_e32 v26, 0, v25
	v_pk_mul_f32 v[116:117], v[116:117], v[56:57]
	v_pk_mul_f32 v[118:119], v[118:119], v[58:59]
	v_pk_mul_f32 v[120:121], v[120:121], v[60:61]
	v_pk_mul_f32 v[122:123], v[122:123], v[62:63]
	ds_write_b128 v22, v[72:75] offset:256
	ds_write_b128 v22, v[76:79] offset:272
	ds_write_b128 v22, v[80:83] offset:1024
	ds_write_b128 v22, v[84:87] offset:1040
	v_pk_mul_f32 v[100:101], v[100:101], v[26:27] op_sel_hi:[1,0]
	v_pk_mul_f32 v[102:103], v[102:103], v[26:27] op_sel_hi:[1,0]
	v_pk_mul_f32 v[104:105], v[104:105], v[26:27] op_sel_hi:[1,0]
	v_pk_mul_f32 v[106:107], v[106:107], v[26:27] op_sel_hi:[1,0]
	ds_write_b128 v22, v[88:91] offset:1280
	ds_write_b128 v22, v[92:95] offset:1296
	ds_write_b128 v22, v[116:119] offset:768
	ds_write_b128 v22, v[120:123] offset:784
	v_pk_mul_f32 v[108:109], v[100:101], v[64:65] neg_lo:[1,0] neg_hi:[1,0]
	v_pk_mul_f32 v[110:111], v[102:103], v[66:67] neg_lo:[1,0] neg_hi:[1,0]
	v_pk_mul_f32 v[112:113], v[104:105], v[68:69] neg_lo:[1,0] neg_hi:[1,0]
	v_pk_mul_f32 v[114:115], v[106:107], v[70:71] neg_lo:[1,0] neg_hi:[1,0]
	ds_write_b128 v22, v[100:103]
	ds_write_b128 v22, v[104:107] offset:16
	ds_write_b128 v22, v[108:111] offset:512
	ds_write_b128 v22, v[112:115] offset:528
	v_add_u32_e32 v22, s54, v22
	s_sub_u32 s54, 0, s54
.Lsc_pskip:
	s_cmp_eq_u32 s46, 0
	s_cbranch_scc1 .Lsc_pnoflush
	s_sub_u32 s76, s46, 1
	s_sub_u32 s60, s76, 8
	s_cmp_lt_u32 s76, 8
	s_cselect_b32 s60, s76, s60
	s_lshl_b32 s60, s60, 5
	s_lshl_b32 s61, s37, 8
	s_add_u32 s61, s61, 0x8000
	s_lshl_b32 s59, s37, 12
	s_cmp_lt_u32 s76, 8
	s_cselect_b32 s59, s61, s59
	s_movk_i32 s61, 0xfe0
	s_cselect_b32 s61, 0xe0, s61
	s_sub_u32 s61, s61, s60
	s_cmp_eq_u32 s31, 0
	s_cselect_b32 s60, s60, s61
	s_add_u32 s59, s59, s60
	s_lshl_b32 s60, s59, 10
	s_add_u32 s56, s44, s60
	s_addc_u32 s57, s45, 0
	ds_read_b128 v[28:31], v23
	s_waitcnt lgkmcnt(0)
	v_cvt_pk_bf16_f32 v28, v28, v29
	v_cvt_pk_bf16_f32 v29, v30, v31
	global_store_dwordx2 v24, v[28:29], s[56:57]
	v_xor_b32_e32 v23, 0x1000, v23
.Lsc_pnoflush:
	s_add_u32 s46, s46, 1
	s_cmp_lt_u32 s46, 136
	s_waitcnt lgkmcnt(0)
	s_barrier
	s_cbranch_scc1 .Lsc_ploop
	s_mov_b32 s76, 135
	s_sub_u32 s60, s76, 8
	s_cmp_lt_u32 s76, 8
	s_cselect_b32 s60, s76, s60
	s_lshl_b32 s60, s60, 5
	s_lshl_b32 s61, s37, 8
	s_add_u32 s61, s61, 0x8000
	s_lshl_b32 s59, s37, 12
	s_cmp_lt_u32 s76, 8
	s_cselect_b32 s59, s61, s59
	s_movk_i32 s61, 0xfe0
	s_cselect_b32 s61, 0xe0, s61
	s_sub_u32 s61, s61, s60
	s_cmp_eq_u32 s31, 0
	s_cselect_b32 s60, s60, s61
	s_add_u32 s59, s59, s60
	s_lshl_b32 s60, s59, 10
	s_add_u32 s56, s44, s60
	s_addc_u32 s57, s45, 0
	ds_read_b128 v[28:31], v23
	s_waitcnt lgkmcnt(0)
	v_cvt_pk_bf16_f32 v28, v28, v29
	v_cvt_pk_bf16_f32 v29, v30, v31
	global_store_dwordx2 v24, v[28:29], s[56:57]
	v_xor_b32_e32 v23, 0x1000, v23
	s_branch .LBB0_192
.Lsc_consumer:
	s_lshl_b32 s58, s47, 3
	v_add_u32_e32 v122, s58, v122
	v_lshlrev_b32_e32 v117, 5, v121
	s_lshl_b32 s58, s30, 7
	v_lshl_add_u32 v118, v122, 2, s58
	v_lshlrev_b32_e32 v119, 7, v121
	v_lshl_add_u32 v119, v122, 2, v119
	v_add_u32_e32 v119, 0x18000, v119
	v_cmp_eq_u32_e64 s[62:63], 0, v121
	v_cmp_eq_u32_e64 s[64:65], 1, v121
	v_cmp_eq_u32_e64 s[66:67], 2, v121
	v_cmp_eq_u32_e64 s[68:69], 3, v121
	v_cmp_eq_u32_e64 s[70:71], 4, v121
	v_cmp_eq_u32_e64 s[0:1], 5, v121
	v_cmp_eq_u32_e64 s[96:97], 6, v121
	v_cmp_eq_u32_e64 vcc, 7, v121
	v_mov_b32_e32 v0, 0
	v_mov_b32_e32 v1, 0
	v_mov_b32_e32 v2, 0
	v_mov_b32_e32 v3, 0
	v_mov_b32_e32 v4, 0
	v_mov_b32_e32 v5, 0
	v_mov_b32_e32 v6, 0
	v_mov_b32_e32 v7, 0
	v_mov_b32_e32 v116, 0
	v_mov_b32_e32 v114, 0
	s_barrier
	s_barrier
; DEV void scan_tile(const Params& p, int l, int tile, char* smem) {
;     ...
;       const float* cb = arr + buf * 32 * 384;
;       const int vo = 320 + half * 32 + w * 8 + r8;
;       float* yw = ybuf + buf * 1024 + cg * 32 + w * 8 + r8;
;       auto ldops = [&](ScanOps& o, int sl) {
;         const f32x4* b4 = (const f32x4*)(cb + sl * 384);
;         o.nkk0 = b4[cg * 2]; o.nkk1 = b4[cg * 2 + 1];
;         o.w0 = b4[16 + cg * 2]; o.w1 = b4[16 + cg * 2 + 1];
;         o.kka0 = b4[32 + cg * 2]; o.kka1 = b4[32 + cg * 2 + 1];
;         o.kd0 = b4[48 + cg * 2]; o.kd1 = b4[48 + cg * 2 + 1];
;         o.r0 = b4[64 + cg * 2]; o.r1 = b4[64 + cg * 2 + 1];
;         o.v = cb[sl * 384 + vo];
;       };
;       float ykeep = 0.f;
;       auto step = [&](const ScanOps& o, int sl) {
;         const f32x4 sA = S0 * o.nkk0 + S1 * o.nkk1;
;         const float sa = red8((sA[0] + sA[1]) + (sA[2] + sA[3]));
;         S0 = S0 * o.w0 + (o.kka0 * sa + o.kd0 * o.v);
;         S1 = S1 * o.w1 + (o.kka1 * sa + o.kd1 * o.v);
;         const f32x4 yA = S0 * o.r0 + S1 * o.r1;
;         const float y = red8((yA[0] + yA[1]) + (yA[2] + yA[3]));
;         ykeep = (cg == (sl & 7)) ? y : ykeep;
;       };
;       ScanOps oa, ob;
;       ldops(oa, 0);
; #pragma unroll
;       for (int s8 = 0; s8 < 32; s8 += 8) {
; #pragma unroll
;         for (int q = 0; q < 8; q += 2) {
;           ldops(ob, s8 + q + 1);
;           step(oa, s8 + q);
;           ldops(oa, (s8 + q + 2) & 31);
;           step(ob, s8 + q + 1);
;         }
;         yw[s8 * 32] = ykeep;
;       }
.Lsc_cloop:
	ds_read_b128 v[8:11], v117 offset:0
	ds_read_b128 v[12:15], v117 offset:16
	ds_read_b128 v[16:19], v117 offset:256
	ds_read_b128 v[20:23], v117 offset:272
	ds_read_b128 v[24:27], v117 offset:512
	ds_read_b128 v[28:31], v117 offset:528
	ds_read_b128 v[32:35], v117 offset:768
	ds_read_b128 v[36:39], v117 offset:784
	ds_read_b128 v[40:43], v117 offset:1024
	ds_read_b128 v[44:47], v117 offset:1040
	ds_read2st64_b32 v[88:89], v118 offset0:5 offset1:11
	s_waitcnt lgkmcnt(0)
	ds_read_b128 v[48:51], v117 offset:1536
	ds_read_b128 v[52:55], v117 offset:1552
	ds_read_b128 v[56:59], v117 offset:1792
	ds_read_b128 v[60:63], v117 offset:1808
	ds_read_b128 v[64:67], v117 offset:2048
	ds_read_b128 v[68:71], v117 offset:2064
	ds_read_b128 v[72:75], v117 offset:2304
	ds_read_b128 v[76:79], v117 offset:2320
	ds_read_b128 v[80:83], v117 offset:2560
	ds_read_b128 v[84:87], v117 offset:2576
	v_pk_mul_f32 v[92:93], v[0:1], v[8:9]
	v_pk_mul_f32 v[94:95], v[2:3], v[10:11]
	v_pk_fma_f32 v[92:93], v[4:5], v[12:13], v[92:93]
	v_pk_fma_f32 v[94:95], v[6:7], v[14:15], v[94:95]
	v_add_f32_dpp v114, v114, v114 quad_perm:[1,0,3,2] row_mask:0xf bank_mask:0xf bound_ctrl:1
	v_pk_add_f32 v[92:93], v[92:93], v[94:95]
	v_pk_mul_f32 v[102:103], v[32:33], v[88:89] op_sel_hi:[1,0]
	v_add_f32_dpp v114, v114, v114 quad_perm:[2,3,0,1] row_mask:0xf bank_mask:0xf bound_ctrl:1
	v_add_f32_e32 v110, v92, v93
	v_pk_mul_f32 v[104:105], v[34:35], v[88:89] op_sel_hi:[1,0]
	v_add_f32_dpp v115, v114, v114 row_half_mirror row_mask:0xf bank_mask:0xf bound_ctrl:1
	v_pk_mul_f32 v[106:107], v[36:37], v[88:89] op_sel_hi:[1,0]
	v_add_f32_dpp v110, v110, v110 quad_perm:[1,0,3,2] row_mask:0xf bank_mask:0xf bound_ctrl:1
	v_pk_mul_f32 v[108:109], v[38:39], v[88:89] op_sel_hi:[1,0]
	v_pk_fma_f32 v[0:1], v[0:1], v[16:17], v[102:103]
	v_add_f32_dpp v110, v110, v110 quad_perm:[2,3,0,1] row_mask:0xf bank_mask:0xf bound_ctrl:1
	v_pk_fma_f32 v[2:3], v[2:3], v[18:19], v[104:105]
	v_pk_fma_f32 v[4:5], v[4:5], v[20:21], v[106:107]
	v_add_f32_dpp v112, v110, v110 row_half_mirror row_mask:0xf bank_mask:0xf bound_ctrl:1
	v_pk_fma_f32 v[6:7], v[6:7], v[22:23], v[108:109]
	v_cndmask_b32_e64 v116, v116, v115, vcc
	v_pk_fma_f32 v[0:1], v[24:25], v[112:113], v[0:1] op_sel_hi:[1,0,1]
	v_pk_fma_f32 v[2:3], v[26:27], v[112:113], v[2:3] op_sel_hi:[1,0,1]
	v_pk_fma_f32 v[4:5], v[28:29], v[112:113], v[4:5] op_sel_hi:[1,0,1]
	v_pk_fma_f32 v[6:7], v[30:31], v[112:113], v[6:7] op_sel_hi:[1,0,1]
	v_pk_mul_f32 v[98:99], v[0:1], v[40:41]
	v_pk_mul_f32 v[100:101], v[2:3], v[42:43]
	v_pk_fma_f32 v[98:99], v[4:5], v[44:45], v[98:99]
	v_pk_fma_f32 v[100:101], v[6:7], v[46:47], v[100:101]
	v_pk_add_f32 v[98:99], v[98:99], v[100:101]
	v_add_f32_e32 v114, v98, v99
	s_waitcnt lgkmcnt(0)
	ds_read_b128 v[8:11], v117 offset:3072
	ds_read_b128 v[12:15], v117 offset:3088
	ds_read_b128 v[16:19], v117 offset:3328
	ds_read_b128 v[20:23], v117 offset:3344
	ds_read_b128 v[24:27], v117 offset:3584
	ds_read_b128 v[28:31], v117 offset:3600
	ds_read_b128 v[32:35], v117 offset:3840
	ds_read_b128 v[36:39], v117 offset:3856
	ds_read_b128 v[40:43], v117 offset:4096
	ds_read_b128 v[44:47], v117 offset:4112
	ds_read2st64_b32 v[90:91], v118 offset0:17 offset1:23
	v_pk_mul_f32 v[92:93], v[0:1], v[48:49]
	v_pk_mul_f32 v[94:95], v[2:3], v[50:51]
	v_pk_fma_f32 v[92:93], v[4:5], v[52:53], v[92:93]
	v_pk_fma_f32 v[94:95], v[6:7], v[54:55], v[94:95]
	v_add_f32_dpp v114, v114, v114 quad_perm:[1,0,3,2] row_mask:0xf bank_mask:0xf bound_ctrl:1
	v_pk_add_f32 v[92:93], v[92:93], v[94:95]
	v_pk_mul_f32 v[102:103], v[72:73], v[88:89] op_sel:[0,1] op_sel_hi:[1,1]
	v_add_f32_dpp v114, v114, v114 quad_perm:[2,3,0,1] row_mask:0xf bank_mask:0xf bound_ctrl:1
	v_add_f32_e32 v110, v92, v93
	v_pk_mul_f32 v[104:105], v[74:75], v[88:89] op_sel:[0,1] op_sel_hi:[1,1]
	v_add_f32_dpp v115, v114, v114 row_half_mirror row_mask:0xf bank_mask:0xf bound_ctrl:1
	v_pk_mul_f32 v[106:107], v[76:77], v[88:89] op_sel:[0,1] op_sel_hi:[1,1]
	v_add_f32_dpp v110, v110, v110 quad_perm:[1,0,3,2] row_mask:0xf bank_mask:0xf bound_ctrl:1
	v_pk_mul_f32 v[108:109], v[78:79], v[88:89] op_sel:[0,1] op_sel_hi:[1,1]
	v_pk_fma_f32 v[0:1], v[0:1], v[56:57], v[102:103]
	v_add_f32_dpp v110, v110, v110 quad_perm:[2,3,0,1] row_mask:0xf bank_mask:0xf bound_ctrl:1
	v_pk_fma_f32 v[2:3], v[2:3], v[58:59], v[104:105]
	v_pk_fma_f32 v[4:5], v[4:5], v[60:61], v[106:107]
	v_add_f32_dpp v112, v110, v110 row_half_mirror row_mask:0xf bank_mask:0xf bound_ctrl:1
	v_pk_fma_f32 v[6:7], v[6:7], v[62:63], v[108:109]
	v_cndmask_b32_e64 v116, v116, v115, s[62:63]
	v_pk_fma_f32 v[0:1], v[64:65], v[112:113], v[0:1] op_sel_hi:[1,0,1]
	v_pk_fma_f32 v[2:3], v[66:67], v[112:113], v[2:3] op_sel_hi:[1,0,1]
	v_pk_fma_f32 v[4:5], v[68:69], v[112:113], v[4:5] op_sel_hi:[1,0,1]
	v_pk_fma_f32 v[6:7], v[70:71], v[112:113], v[6:7] op_sel_hi:[1,0,1]
	v_pk_mul_f32 v[98:99], v[0:1], v[80:81]
	v_pk_mul_f32 v[100:101], v[2:3], v[82:83]
	v_pk_fma_f32 v[98:99], v[4:5], v[84:85], v[98:99]
	v_pk_fma_f32 v[100:101], v[6:7], v[86:87], v[100:101]
	v_pk_add_f32 v[98:99], v[98:99], v[100:101]
	v_add_f32_e32 v114, v98, v99
	s_waitcnt lgkmcnt(0)
; DEV void scan_tile(const Params& p, int l, int tile, char* smem) {
;     ...
;       const float* cb = arr + buf * 32 * 384;
;       const int vo = 320 + half * 32 + w * 8 + r8;
;       float* yw = ybuf + buf * 1024 + cg * 32 + w * 8 + r8;
;       auto ldops = [&](ScanOps& o, int sl) {
;         const f32x4* b4 = (const f32x4*)(cb + sl * 384);
;         o.nkk0 = b4[cg * 2]; o.nkk1 = b4[cg * 2 + 1];
;         o.w0 = b4[16 + cg * 2]; o.w1 = b4[16 + cg * 2 + 1];
;         o.kka0 = b4[32 + cg * 2]; o.kka1 = b4[32 + cg * 2 + 1];
;         o.kd0 = b4[48 + cg * 2]; o.kd1 = b4[48 + cg * 2 + 1];
;         o.r0 = b4[64 + cg * 2]; o.r1 = b4[64 + cg * 2 + 1];
;         o.v = cb[sl * 384 + vo];
;       };
;       float ykeep = 0.f;
;       auto step = [&](const ScanOps& o, int sl) {
;         const f32x4 sA = S0 * o.nkk0 + S1 * o.nkk1;
;         const float sa = red8((sA[0] + sA[1]) + (sA[2] + sA[3]));
;         S0 = S0 * o.w0 + (o.kka0 * sa + o.kd0 * o.v);
;         S1 = S1 * o.w1 + (o.kka1 * sa + o.kd1 * o.v);
;         const f32x4 yA = S0 * o.r0 + S1 * o.r1;
;         const float y = red8((yA[0] + yA[1]) + (yA[2] + yA[3]));
;         ykeep = (cg == (sl & 7)) ? y : ykeep;
;       };
;       ScanOps oa, ob;
;       ldops(oa, 0);
; #pragma unroll
;       for (int s8 = 0; s8 < 32; s8 += 8) {
; #pragma unroll
;         for (int q = 0; q < 8; q += 2) {
;           ldops(ob, s8 + q + 1);
;           step(oa, s8 + q);
;           ldops(oa, (s8 + q + 2) & 31);
;           step(ob, s8 + q + 1);
;         }
;         yw[s8 * 32] = ykeep;
;       }
	ds_read_b128 v[48:51], v117 offset:4608
	ds_read_b128 v[52:55], v117 offset:4624
	ds_read_b128 v[56:59], v117 offset:4864
	ds_read_b128 v[60:63], v117 offset:4880
	ds_read_b128 v[64:67], v117 offset:5120
	ds_read_b128 v[68:71], v117 offset:5136
	ds_read_b128 v[72:75], v117 offset:5376
	ds_read_b128 v[76:79], v117 offset:5392
	ds_read_b128 v[80:83], v117 offset:5632
	ds_read_b128 v[84:87], v117 offset:5648
	v_pk_mul_f32 v[92:93], v[0:1], v[8:9]
	v_pk_mul_f32 v[94:95], v[2:3], v[10:11]
	v_pk_fma_f32 v[92:93], v[4:5], v[12:13], v[92:93]
	v_pk_fma_f32 v[94:95], v[6:7], v[14:15], v[94:95]
	v_add_f32_dpp v114, v114, v114 quad_perm:[1,0,3,2] row_mask:0xf bank_mask:0xf bound_ctrl:1
	v_pk_add_f32 v[92:93], v[92:93], v[94:95]
	v_pk_mul_f32 v[102:103], v[32:33], v[90:91] op_sel_hi:[1,0]
	v_add_f32_dpp v114, v114, v114 quad_perm:[2,3,0,1] row_mask:0xf bank_mask:0xf bound_ctrl:1
	v_add_f32_e32 v110, v92, v93
	v_pk_mul_f32 v[104:105], v[34:35], v[90:91] op_sel_hi:[1,0]
	v_add_f32_dpp v115, v114, v114 row_half_mirror row_mask:0xf bank_mask:0xf bound_ctrl:1
	v_pk_mul_f32 v[106:107], v[36:37], v[90:91] op_sel_hi:[1,0]
	v_add_f32_dpp v110, v110, v110 quad_perm:[1,0,3,2] row_mask:0xf bank_mask:0xf bound_ctrl:1
	v_pk_mul_f32 v[108:109], v[38:39], v[90:91] op_sel_hi:[1,0]
	v_pk_fma_f32 v[0:1], v[0:1], v[16:17], v[102:103]
	v_add_f32_dpp v110, v110, v110 quad_perm:[2,3,0,1] row_mask:0xf bank_mask:0xf bound_ctrl:1
	v_pk_fma_f32 v[2:3], v[2:3], v[18:19], v[104:105]
	v_pk_fma_f32 v[4:5], v[4:5], v[20:21], v[106:107]
	v_add_f32_dpp v112, v110, v110 row_half_mirror row_mask:0xf bank_mask:0xf bound_ctrl:1
	v_pk_fma_f32 v[6:7], v[6:7], v[22:23], v[108:109]
	v_cndmask_b32_e64 v116, v116, v115, s[64:65]
	v_pk_fma_f32 v[0:1], v[24:25], v[112:113], v[0:1] op_sel_hi:[1,0,1]
	v_pk_fma_f32 v[2:3], v[26:27], v[112:113], v[2:3] op_sel_hi:[1,0,1]
	v_pk_fma_f32 v[4:5], v[28:29], v[112:113], v[4:5] op_sel_hi:[1,0,1]
	v_pk_fma_f32 v[6:7], v[30:31], v[112:113], v[6:7] op_sel_hi:[1,0,1]
	v_pk_mul_f32 v[98:99], v[0:1], v[40:41]
	v_pk_mul_f32 v[100:101], v[2:3], v[42:43]
	v_pk_fma_f32 v[98:99], v[4:5], v[44:45], v[98:99]
	v_pk_fma_f32 v[100:101], v[6:7], v[46:47], v[100:101]
	v_pk_add_f32 v[98:99], v[98:99], v[100:101]
	v_add_f32_e32 v114, v98, v99
	s_waitcnt lgkmcnt(0)
	ds_read_b128 v[8:11], v117 offset:6144
	ds_read_b128 v[12:15], v117 offset:6160
	ds_read_b128 v[16:19], v117 offset:6400
	ds_read_b128 v[20:23], v117 offset:6416
	ds_read_b128 v[24:27], v117 offset:6656
	ds_read_b128 v[28:31], v117 offset:6672
	ds_read_b128 v[32:35], v117 offset:6912
	ds_read_b128 v[36:39], v117 offset:6928
	ds_read_b128 v[40:43], v117 offset:7168
	ds_read_b128 v[44:47], v117 offset:7184
	ds_read2st64_b32 v[88:89], v118 offset0:29 offset1:35
	v_pk_mul_f32 v[92:93], v[0:1], v[48:49]
	v_pk_mul_f32 v[94:95], v[2:3], v[50:51]
	v_pk_fma_f32 v[92:93], v[4:5], v[52:53], v[92:93]
	v_pk_fma_f32 v[94:95], v[6:7], v[54:55], v[94:95]
	v_add_f32_dpp v114, v114, v114 quad_perm:[1,0,3,2] row_mask:0xf bank_mask:0xf bound_ctrl:1
	v_pk_add_f32 v[92:93], v[92:93], v[94:95]
	v_pk_mul_f32 v[102:103], v[72:73], v[90:91] op_sel:[0,1] op_sel_hi:[1,1]
	v_add_f32_dpp v114, v114, v114 quad_perm:[2,3,0,1] row_mask:0xf bank_mask:0xf bound_ctrl:1
	v_add_f32_e32 v110, v92, v93
	v_pk_mul_f32 v[104:105], v[74:75], v[90:91] op_sel:[0,1] op_sel_hi:[1,1]
	v_add_f32_dpp v115, v114, v114 row_half_mirror row_mask:0xf bank_mask:0xf bound_ctrl:1
	v_pk_mul_f32 v[106:107], v[76:77], v[90:91] op_sel:[0,1] op_sel_hi:[1,1]
	v_add_f32_dpp v110, v110, v110 quad_perm:[1,0,3,2] row_mask:0xf bank_mask:0xf bound_ctrl:1
	v_pk_mul_f32 v[108:109], v[78:79], v[90:91] op_sel:[0,1] op_sel_hi:[1,1]
	v_pk_fma_f32 v[0:1], v[0:1], v[56:57], v[102:103]
	v_add_f32_dpp v110, v110, v110 quad_perm:[2,3,0,1] row_mask:0xf bank_mask:0xf bound_ctrl:1
	v_pk_fma_f32 v[2:3], v[2:3], v[58:59], v[104:105]
	v_pk_fma_f32 v[4:5], v[4:5], v[60:61], v[106:107]
	v_add_f32_dpp v112, v110, v110 row_half_mirror row_mask:0xf bank_mask:0xf bound_ctrl:1
	v_pk_fma_f32 v[6:7], v[6:7], v[62:63], v[108:109]
	v_cndmask_b32_e64 v116, v116, v115, s[66:67]
	v_pk_fma_f32 v[0:1], v[64:65], v[112:113], v[0:1] op_sel_hi:[1,0,1]
	v_pk_fma_f32 v[2:3], v[66:67], v[112:113], v[2:3] op_sel_hi:[1,0,1]
	v_pk_fma_f32 v[4:5], v[68:69], v[112:113], v[4:5] op_sel_hi:[1,0,1]
	v_pk_fma_f32 v[6:7], v[70:71], v[112:113], v[6:7] op_sel_hi:[1,0,1]
	v_pk_mul_f32 v[98:99], v[0:1], v[80:81]
	v_pk_mul_f32 v[100:101], v[2:3], v[82:83]
	v_pk_fma_f32 v[98:99], v[4:5], v[84:85], v[98:99]
	v_pk_fma_f32 v[100:101], v[6:7], v[86:87], v[100:101]
	v_pk_add_f32 v[98:99], v[98:99], v[100:101]
	v_add_f32_e32 v114, v98, v99
	s_waitcnt lgkmcnt(0)
; DEV void scan_tile(const Params& p, int l, int tile, char* smem) {
;     ...
;       const float* cb = arr + buf * 32 * 384;
;       const int vo = 320 + half * 32 + w * 8 + r8;
;       float* yw = ybuf + buf * 1024 + cg * 32 + w * 8 + r8;
;       auto ldops = [&](ScanOps& o, int sl) {
;         const f32x4* b4 = (const f32x4*)(cb + sl * 384);
;         o.nkk0 = b4[cg * 2]; o.nkk1 = b4[cg * 2 + 1];
;         o.w0 = b4[16 + cg * 2]; o.w1 = b4[16 + cg * 2 + 1];
;         o.kka0 = b4[32 + cg * 2]; o.kka1 = b4[32 + cg * 2 + 1];
;         o.kd0 = b4[48 + cg * 2]; o.kd1 = b4[48 + cg * 2 + 1];
;         o.r0 = b4[64 + cg * 2]; o.r1 = b4[64 + cg * 2 + 1];
;         o.v = cb[sl * 384 + vo];
;       };
;       float ykeep = 0.f;
;       auto step = [&](const ScanOps& o, int sl) {
;         const f32x4 sA = S0 * o.nkk0 + S1 * o.nkk1;
;         const float sa = red8((sA[0] + sA[1]) + (sA[2] + sA[3]));
;         S0 = S0 * o.w0 + (o.kka0 * sa + o.kd0 * o.v);
;         S1 = S1 * o.w1 + (o.kka1 * sa + o.kd1 * o.v);
;         const f32x4 yA = S0 * o.r0 + S1 * o.r1;
;         const float y = red8((yA[0] + yA[1]) + (yA[2] + yA[3]));
;         ykeep = (cg == (sl & 7)) ? y : ykeep;
;       };
;       ScanOps oa, ob;
;       ldops(oa, 0);
; #pragma unroll
;       for (int s8 = 0; s8 < 32; s8 += 8) {
; #pragma unroll
;         for (int q = 0; q < 8; q += 2) {
;           ldops(ob, s8 + q + 1);
;           step(oa, s8 + q);
;           ldops(oa, (s8 + q + 2) & 31);
;           step(ob, s8 + q + 1);
;         }
;         yw[s8 * 32] = ykeep;
;       }
	ds_read_b128 v[48:51], v117 offset:7680
	ds_read_b128 v[52:55], v117 offset:7696
	ds_read_b128 v[56:59], v117 offset:7936
	ds_read_b128 v[60:63], v117 offset:7952
	ds_read_b128 v[64:67], v117 offset:8192
	ds_read_b128 v[68:71], v117 offset:8208
	ds_read_b128 v[72:75], v117 offset:8448
	ds_read_b128 v[76:79], v117 offset:8464
	ds_read_b128 v[80:83], v117 offset:8704
	ds_read_b128 v[84:87], v117 offset:8720
	v_pk_mul_f32 v[92:93], v[0:1], v[8:9]
	v_pk_mul_f32 v[94:95], v[2:3], v[10:11]
	v_pk_fma_f32 v[92:93], v[4:5], v[12:13], v[92:93]
	v_pk_fma_f32 v[94:95], v[6:7], v[14:15], v[94:95]
	v_add_f32_dpp v114, v114, v114 quad_perm:[1,0,3,2] row_mask:0xf bank_mask:0xf bound_ctrl:1
	v_pk_add_f32 v[92:93], v[92:93], v[94:95]
	v_pk_mul_f32 v[102:103], v[32:33], v[88:89] op_sel_hi:[1,0]
	v_add_f32_dpp v114, v114, v114 quad_perm:[2,3,0,1] row_mask:0xf bank_mask:0xf bound_ctrl:1
	v_add_f32_e32 v110, v92, v93
	v_pk_mul_f32 v[104:105], v[34:35], v[88:89] op_sel_hi:[1,0]
	v_add_f32_dpp v115, v114, v114 row_half_mirror row_mask:0xf bank_mask:0xf bound_ctrl:1
	v_pk_mul_f32 v[106:107], v[36:37], v[88:89] op_sel_hi:[1,0]
	v_add_f32_dpp v110, v110, v110 quad_perm:[1,0,3,2] row_mask:0xf bank_mask:0xf bound_ctrl:1
	v_pk_mul_f32 v[108:109], v[38:39], v[88:89] op_sel_hi:[1,0]
	v_pk_fma_f32 v[0:1], v[0:1], v[16:17], v[102:103]
	v_add_f32_dpp v110, v110, v110 quad_perm:[2,3,0,1] row_mask:0xf bank_mask:0xf bound_ctrl:1
	v_pk_fma_f32 v[2:3], v[2:3], v[18:19], v[104:105]
	v_pk_fma_f32 v[4:5], v[4:5], v[20:21], v[106:107]
	v_add_f32_dpp v112, v110, v110 row_half_mirror row_mask:0xf bank_mask:0xf bound_ctrl:1
	v_pk_fma_f32 v[6:7], v[6:7], v[22:23], v[108:109]
	v_cndmask_b32_e64 v116, v116, v115, s[68:69]
	v_pk_fma_f32 v[0:1], v[24:25], v[112:113], v[0:1] op_sel_hi:[1,0,1]
	v_pk_fma_f32 v[2:3], v[26:27], v[112:113], v[2:3] op_sel_hi:[1,0,1]
	v_pk_fma_f32 v[4:5], v[28:29], v[112:113], v[4:5] op_sel_hi:[1,0,1]
	v_pk_fma_f32 v[6:7], v[30:31], v[112:113], v[6:7] op_sel_hi:[1,0,1]
	v_pk_mul_f32 v[98:99], v[0:1], v[40:41]
	v_pk_mul_f32 v[100:101], v[2:3], v[42:43]
	v_pk_fma_f32 v[98:99], v[4:5], v[44:45], v[98:99]
	v_pk_fma_f32 v[100:101], v[6:7], v[46:47], v[100:101]
	v_pk_add_f32 v[98:99], v[98:99], v[100:101]
	v_add_f32_e32 v114, v98, v99
	s_waitcnt lgkmcnt(0)
	ds_read_b128 v[8:11], v117 offset:9216
	ds_read_b128 v[12:15], v117 offset:9232
	ds_read_b128 v[16:19], v117 offset:9472
	ds_read_b128 v[20:23], v117 offset:9488
	ds_read_b128 v[24:27], v117 offset:9728
	ds_read_b128 v[28:31], v117 offset:9744
	ds_read_b128 v[32:35], v117 offset:9984
	ds_read_b128 v[36:39], v117 offset:10000
	ds_read_b128 v[40:43], v117 offset:10240
	ds_read_b128 v[44:47], v117 offset:10256
	ds_read2st64_b32 v[90:91], v118 offset0:41 offset1:47
	v_pk_mul_f32 v[92:93], v[0:1], v[48:49]
	v_pk_mul_f32 v[94:95], v[2:3], v[50:51]
	v_pk_fma_f32 v[92:93], v[4:5], v[52:53], v[92:93]
	v_pk_fma_f32 v[94:95], v[6:7], v[54:55], v[94:95]
	v_add_f32_dpp v114, v114, v114 quad_perm:[1,0,3,2] row_mask:0xf bank_mask:0xf bound_ctrl:1
	v_pk_add_f32 v[92:93], v[92:93], v[94:95]
	v_pk_mul_f32 v[102:103], v[72:73], v[88:89] op_sel:[0,1] op_sel_hi:[1,1]
	v_add_f32_dpp v114, v114, v114 quad_perm:[2,3,0,1] row_mask:0xf bank_mask:0xf bound_ctrl:1
	v_add_f32_e32 v110, v92, v93
	v_pk_mul_f32 v[104:105], v[74:75], v[88:89] op_sel:[0,1] op_sel_hi:[1,1]
	v_add_f32_dpp v115, v114, v114 row_half_mirror row_mask:0xf bank_mask:0xf bound_ctrl:1
	v_pk_mul_f32 v[106:107], v[76:77], v[88:89] op_sel:[0,1] op_sel_hi:[1,1]
	v_add_f32_dpp v110, v110, v110 quad_perm:[1,0,3,2] row_mask:0xf bank_mask:0xf bound_ctrl:1
	v_pk_mul_f32 v[108:109], v[78:79], v[88:89] op_sel:[0,1] op_sel_hi:[1,1]
	v_pk_fma_f32 v[0:1], v[0:1], v[56:57], v[102:103]
	v_add_f32_dpp v110, v110, v110 quad_perm:[2,3,0,1] row_mask:0xf bank_mask:0xf bound_ctrl:1
	v_pk_fma_f32 v[2:3], v[2:3], v[58:59], v[104:105]
	v_pk_fma_f32 v[4:5], v[4:5], v[60:61], v[106:107]
	v_add_f32_dpp v112, v110, v110 row_half_mirror row_mask:0xf bank_mask:0xf bound_ctrl:1
	v_pk_fma_f32 v[6:7], v[6:7], v[62:63], v[108:109]
	v_cndmask_b32_e64 v116, v116, v115, s[70:71]
	v_pk_fma_f32 v[0:1], v[64:65], v[112:113], v[0:1] op_sel_hi:[1,0,1]
	v_pk_fma_f32 v[2:3], v[66:67], v[112:113], v[2:3] op_sel_hi:[1,0,1]
	v_pk_fma_f32 v[4:5], v[68:69], v[112:113], v[4:5] op_sel_hi:[1,0,1]
	v_pk_fma_f32 v[6:7], v[70:71], v[112:113], v[6:7] op_sel_hi:[1,0,1]
	v_pk_mul_f32 v[98:99], v[0:1], v[80:81]
	v_pk_mul_f32 v[100:101], v[2:3], v[82:83]
	v_pk_fma_f32 v[98:99], v[4:5], v[84:85], v[98:99]
	v_pk_fma_f32 v[100:101], v[6:7], v[86:87], v[100:101]
	v_pk_add_f32 v[98:99], v[98:99], v[100:101]
	v_add_f32_e32 v114, v98, v99
	s_waitcnt lgkmcnt(0)
; DEV void scan_tile(const Params& p, int l, int tile, char* smem) {
;     ...
;       const float* cb = arr + buf * 32 * 384;
;       const int vo = 320 + half * 32 + w * 8 + r8;
;       float* yw = ybuf + buf * 1024 + cg * 32 + w * 8 + r8;
;       auto ldops = [&](ScanOps& o, int sl) {
;         const f32x4* b4 = (const f32x4*)(cb + sl * 384);
;         o.nkk0 = b4[cg * 2]; o.nkk1 = b4[cg * 2 + 1];
;         o.w0 = b4[16 + cg * 2]; o.w1 = b4[16 + cg * 2 + 1];
;         o.kka0 = b4[32 + cg * 2]; o.kka1 = b4[32 + cg * 2 + 1];
;         o.kd0 = b4[48 + cg * 2]; o.kd1 = b4[48 + cg * 2 + 1];
;         o.r0 = b4[64 + cg * 2]; o.r1 = b4[64 + cg * 2 + 1];
;         o.v = cb[sl * 384 + vo];
;       };
;       float ykeep = 0.f;
;       auto step = [&](const ScanOps& o, int sl) {
;         const f32x4 sA = S0 * o.nkk0 + S1 * o.nkk1;
;         const float sa = red8((sA[0] + sA[1]) + (sA[2] + sA[3]));
;         S0 = S0 * o.w0 + (o.kka0 * sa + o.kd0 * o.v);
;         S1 = S1 * o.w1 + (o.kka1 * sa + o.kd1 * o.v);
;         const f32x4 yA = S0 * o.r0 + S1 * o.r1;
;         const float y = red8((yA[0] + yA[1]) + (yA[2] + yA[3]));
;         ykeep = (cg == (sl & 7)) ? y : ykeep;
;       };
;       ScanOps oa, ob;
;       ldops(oa, 0);
; #pragma unroll
;       for (int s8 = 0; s8 < 32; s8 += 8) {
; #pragma unroll
;         for (int q = 0; q < 8; q += 2) {
;           ldops(ob, s8 + q + 1);
;           step(oa, s8 + q);
;           ldops(oa, (s8 + q + 2) & 31);
;           step(ob, s8 + q + 1);
;         }
;         yw[s8 * 32] = ykeep;
;       }
	ds_read_b128 v[48:51], v117 offset:10752
	ds_read_b128 v[52:55], v117 offset:10768
	ds_read_b128 v[56:59], v117 offset:11008
	ds_read_b128 v[60:63], v117 offset:11024
	ds_read_b128 v[64:67], v117 offset:11264
	ds_read_b128 v[68:71], v117 offset:11280
	ds_read_b128 v[72:75], v117 offset:11520
	ds_read_b128 v[76:79], v117 offset:11536
	ds_read_b128 v[80:83], v117 offset:11776
	ds_read_b128 v[84:87], v117 offset:11792
	v_pk_mul_f32 v[92:93], v[0:1], v[8:9]
	v_pk_mul_f32 v[94:95], v[2:3], v[10:11]
	v_pk_fma_f32 v[92:93], v[4:5], v[12:13], v[92:93]
	v_pk_fma_f32 v[94:95], v[6:7], v[14:15], v[94:95]
	v_add_f32_dpp v114, v114, v114 quad_perm:[1,0,3,2] row_mask:0xf bank_mask:0xf bound_ctrl:1
	v_pk_add_f32 v[92:93], v[92:93], v[94:95]
	v_pk_mul_f32 v[102:103], v[32:33], v[90:91] op_sel_hi:[1,0]
	v_add_f32_dpp v114, v114, v114 quad_perm:[2,3,0,1] row_mask:0xf bank_mask:0xf bound_ctrl:1
	v_add_f32_e32 v110, v92, v93
	v_pk_mul_f32 v[104:105], v[34:35], v[90:91] op_sel_hi:[1,0]
	v_add_f32_dpp v115, v114, v114 row_half_mirror row_mask:0xf bank_mask:0xf bound_ctrl:1
	v_pk_mul_f32 v[106:107], v[36:37], v[90:91] op_sel_hi:[1,0]
	v_add_f32_dpp v110, v110, v110 quad_perm:[1,0,3,2] row_mask:0xf bank_mask:0xf bound_ctrl:1
	v_pk_mul_f32 v[108:109], v[38:39], v[90:91] op_sel_hi:[1,0]
	v_pk_fma_f32 v[0:1], v[0:1], v[16:17], v[102:103]
	v_add_f32_dpp v110, v110, v110 quad_perm:[2,3,0,1] row_mask:0xf bank_mask:0xf bound_ctrl:1
	v_pk_fma_f32 v[2:3], v[2:3], v[18:19], v[104:105]
	v_pk_fma_f32 v[4:5], v[4:5], v[20:21], v[106:107]
	v_add_f32_dpp v112, v110, v110 row_half_mirror row_mask:0xf bank_mask:0xf bound_ctrl:1
	v_pk_fma_f32 v[6:7], v[6:7], v[22:23], v[108:109]
	v_cndmask_b32_e64 v116, v116, v115, s[0:1]
	v_pk_fma_f32 v[0:1], v[24:25], v[112:113], v[0:1] op_sel_hi:[1,0,1]
	v_pk_fma_f32 v[2:3], v[26:27], v[112:113], v[2:3] op_sel_hi:[1,0,1]
	v_pk_fma_f32 v[4:5], v[28:29], v[112:113], v[4:5] op_sel_hi:[1,0,1]
	v_pk_fma_f32 v[6:7], v[30:31], v[112:113], v[6:7] op_sel_hi:[1,0,1]
	v_pk_mul_f32 v[98:99], v[0:1], v[40:41]
	v_pk_mul_f32 v[100:101], v[2:3], v[42:43]
	v_pk_fma_f32 v[98:99], v[4:5], v[44:45], v[98:99]
	v_pk_fma_f32 v[100:101], v[6:7], v[46:47], v[100:101]
	v_pk_add_f32 v[98:99], v[98:99], v[100:101]
	v_add_f32_e32 v114, v98, v99
	s_waitcnt lgkmcnt(0)
	ds_read_b128 v[8:11], v117 offset:12288
	ds_read_b128 v[12:15], v117 offset:12304
	ds_read_b128 v[16:19], v117 offset:12544
	ds_read_b128 v[20:23], v117 offset:12560
	ds_read_b128 v[24:27], v117 offset:12800
	ds_read_b128 v[28:31], v117 offset:12816
	ds_read_b128 v[32:35], v117 offset:13056
	ds_read_b128 v[36:39], v117 offset:13072
	ds_read_b128 v[40:43], v117 offset:13312
	ds_read_b128 v[44:47], v117 offset:13328
	ds_read2st64_b32 v[88:89], v118 offset0:53 offset1:59
	v_pk_mul_f32 v[92:93], v[0:1], v[48:49]
	v_pk_mul_f32 v[94:95], v[2:3], v[50:51]
	v_pk_fma_f32 v[92:93], v[4:5], v[52:53], v[92:93]
	v_pk_fma_f32 v[94:95], v[6:7], v[54:55], v[94:95]
	v_add_f32_dpp v114, v114, v114 quad_perm:[1,0,3,2] row_mask:0xf bank_mask:0xf bound_ctrl:1
	v_pk_add_f32 v[92:93], v[92:93], v[94:95]
	v_pk_mul_f32 v[102:103], v[72:73], v[90:91] op_sel:[0,1] op_sel_hi:[1,1]
	v_add_f32_dpp v114, v114, v114 quad_perm:[2,3,0,1] row_mask:0xf bank_mask:0xf bound_ctrl:1
	v_add_f32_e32 v110, v92, v93
	v_pk_mul_f32 v[104:105], v[74:75], v[90:91] op_sel:[0,1] op_sel_hi:[1,1]
	v_add_f32_dpp v115, v114, v114 row_half_mirror row_mask:0xf bank_mask:0xf bound_ctrl:1
	v_pk_mul_f32 v[106:107], v[76:77], v[90:91] op_sel:[0,1] op_sel_hi:[1,1]
	v_add_f32_dpp v110, v110, v110 quad_perm:[1,0,3,2] row_mask:0xf bank_mask:0xf bound_ctrl:1
	v_pk_mul_f32 v[108:109], v[78:79], v[90:91] op_sel:[0,1] op_sel_hi:[1,1]
	v_pk_fma_f32 v[0:1], v[0:1], v[56:57], v[102:103]
	v_add_f32_dpp v110, v110, v110 quad_perm:[2,3,0,1] row_mask:0xf bank_mask:0xf bound_ctrl:1
	v_pk_fma_f32 v[2:3], v[2:3], v[58:59], v[104:105]
	v_pk_fma_f32 v[4:5], v[4:5], v[60:61], v[106:107]
	v_add_f32_dpp v112, v110, v110 row_half_mirror row_mask:0xf bank_mask:0xf bound_ctrl:1
	v_pk_fma_f32 v[6:7], v[6:7], v[62:63], v[108:109]
	v_cndmask_b32_e64 v116, v116, v115, s[96:97]
	v_pk_fma_f32 v[0:1], v[64:65], v[112:113], v[0:1] op_sel_hi:[1,0,1]
	v_pk_fma_f32 v[2:3], v[66:67], v[112:113], v[2:3] op_sel_hi:[1,0,1]
	v_pk_fma_f32 v[4:5], v[68:69], v[112:113], v[4:5] op_sel_hi:[1,0,1]
	v_pk_fma_f32 v[6:7], v[70:71], v[112:113], v[6:7] op_sel_hi:[1,0,1]
	v_pk_mul_f32 v[98:99], v[0:1], v[80:81]
	v_pk_mul_f32 v[100:101], v[2:3], v[82:83]
	v_pk_fma_f32 v[98:99], v[4:5], v[84:85], v[98:99]
	v_pk_fma_f32 v[100:101], v[6:7], v[86:87], v[100:101]
	v_pk_add_f32 v[98:99], v[98:99], v[100:101]
	v_add_f32_e32 v114, v98, v99
	s_waitcnt lgkmcnt(0)
; DEV void scan_tile(const Params& p, int l, int tile, char* smem) {
;     ...
;       const float* cb = arr + buf * 32 * 384;
;       const int vo = 320 + half * 32 + w * 8 + r8;
;       float* yw = ybuf + buf * 1024 + cg * 32 + w * 8 + r8;
;       auto ldops = [&](ScanOps& o, int sl) {
;         const f32x4* b4 = (const f32x4*)(cb + sl * 384);
;         o.nkk0 = b4[cg * 2]; o.nkk1 = b4[cg * 2 + 1];
;         o.w0 = b4[16 + cg * 2]; o.w1 = b4[16 + cg * 2 + 1];
;         o.kka0 = b4[32 + cg * 2]; o.kka1 = b4[32 + cg * 2 + 1];
;         o.kd0 = b4[48 + cg * 2]; o.kd1 = b4[48 + cg * 2 + 1];
;         o.r0 = b4[64 + cg * 2]; o.r1 = b4[64 + cg * 2 + 1];
;         o.v = cb[sl * 384 + vo];
;       };
;       float ykeep = 0.f;
;       auto step = [&](const ScanOps& o, int sl) {
;         const f32x4 sA = S0 * o.nkk0 + S1 * o.nkk1;
;         const float sa = red8((sA[0] + sA[1]) + (sA[2] + sA[3]));
;         S0 = S0 * o.w0 + (o.kka0 * sa + o.kd0 * o.v);
;         S1 = S1 * o.w1 + (o.kka1 * sa + o.kd1 * o.v);
;         const f32x4 yA = S0 * o.r0 + S1 * o.r1;
;         const float y = red8((yA[0] + yA[1]) + (yA[2] + yA[3]));
;         ykeep = (cg == (sl & 7)) ? y : ykeep;
;       };
;       ScanOps oa, ob;
;       ldops(oa, 0);
; #pragma unroll
;       for (int s8 = 0; s8 < 32; s8 += 8) {
; #pragma unroll
;         for (int q = 0; q < 8; q += 2) {
;           ldops(ob, s8 + q + 1);
;           step(oa, s8 + q);
;           ldops(oa, (s8 + q + 2) & 31);
;           step(ob, s8 + q + 1);
;         }
;         yw[s8 * 32] = ykeep;
;       }
	ds_read_b128 v[48:51], v117 offset:13824
	ds_read_b128 v[52:55], v117 offset:13840
	ds_read_b128 v[56:59], v117 offset:14080
	ds_read_b128 v[60:63], v117 offset:14096
	ds_read_b128 v[64:67], v117 offset:14336
	ds_read_b128 v[68:71], v117 offset:14352
	ds_read_b128 v[72:75], v117 offset:14592
	ds_read_b128 v[76:79], v117 offset:14608
	ds_read_b128 v[80:83], v117 offset:14848
	ds_read_b128 v[84:87], v117 offset:14864
	v_pk_mul_f32 v[92:93], v[0:1], v[8:9]
	v_pk_mul_f32 v[94:95], v[2:3], v[10:11]
	v_pk_fma_f32 v[92:93], v[4:5], v[12:13], v[92:93]
	v_pk_fma_f32 v[94:95], v[6:7], v[14:15], v[94:95]
	v_add_f32_dpp v114, v114, v114 quad_perm:[1,0,3,2] row_mask:0xf bank_mask:0xf bound_ctrl:1
	v_pk_add_f32 v[92:93], v[92:93], v[94:95]
	v_pk_mul_f32 v[102:103], v[32:33], v[88:89] op_sel_hi:[1,0]
	v_add_f32_dpp v114, v114, v114 quad_perm:[2,3,0,1] row_mask:0xf bank_mask:0xf bound_ctrl:1
	v_add_f32_e32 v110, v92, v93
	v_pk_mul_f32 v[104:105], v[34:35], v[88:89] op_sel_hi:[1,0]
	v_add_f32_dpp v115, v114, v114 row_half_mirror row_mask:0xf bank_mask:0xf bound_ctrl:1
	v_pk_mul_f32 v[106:107], v[36:37], v[88:89] op_sel_hi:[1,0]
	v_add_f32_dpp v110, v110, v110 quad_perm:[1,0,3,2] row_mask:0xf bank_mask:0xf bound_ctrl:1
	v_pk_mul_f32 v[108:109], v[38:39], v[88:89] op_sel_hi:[1,0]
	v_pk_fma_f32 v[0:1], v[0:1], v[16:17], v[102:103]
	v_add_f32_dpp v110, v110, v110 quad_perm:[2,3,0,1] row_mask:0xf bank_mask:0xf bound_ctrl:1
	v_pk_fma_f32 v[2:3], v[2:3], v[18:19], v[104:105]
	v_pk_fma_f32 v[4:5], v[4:5], v[20:21], v[106:107]
	v_add_f32_dpp v112, v110, v110 row_half_mirror row_mask:0xf bank_mask:0xf bound_ctrl:1
	v_pk_fma_f32 v[6:7], v[6:7], v[22:23], v[108:109]
	v_cndmask_b32_e64 v116, v116, v115, vcc
	ds_write_b32 v119, v116 offset:0
	v_pk_fma_f32 v[0:1], v[24:25], v[112:113], v[0:1] op_sel_hi:[1,0,1]
	v_pk_fma_f32 v[2:3], v[26:27], v[112:113], v[2:3] op_sel_hi:[1,0,1]
	v_pk_fma_f32 v[4:5], v[28:29], v[112:113], v[4:5] op_sel_hi:[1,0,1]
	v_pk_fma_f32 v[6:7], v[30:31], v[112:113], v[6:7] op_sel_hi:[1,0,1]
	v_pk_mul_f32 v[98:99], v[0:1], v[40:41]
	v_pk_mul_f32 v[100:101], v[2:3], v[42:43]
	v_pk_fma_f32 v[98:99], v[4:5], v[44:45], v[98:99]
	v_pk_fma_f32 v[100:101], v[6:7], v[46:47], v[100:101]
	v_pk_add_f32 v[98:99], v[98:99], v[100:101]
	v_add_f32_e32 v114, v98, v99
	s_waitcnt lgkmcnt(1)
	ds_read_b128 v[8:11], v117 offset:15360
	ds_read_b128 v[12:15], v117 offset:15376
	ds_read_b128 v[16:19], v117 offset:15616
	ds_read_b128 v[20:23], v117 offset:15632
	ds_read_b128 v[24:27], v117 offset:15872
	ds_read_b128 v[28:31], v117 offset:15888
	ds_read_b128 v[32:35], v117 offset:16128
	ds_read_b128 v[36:39], v117 offset:16144
	ds_read_b128 v[40:43], v117 offset:16384
	ds_read_b128 v[44:47], v117 offset:16400
	ds_read2st64_b32 v[90:91], v118 offset0:65 offset1:71
	v_pk_mul_f32 v[92:93], v[0:1], v[48:49]
	v_pk_mul_f32 v[94:95], v[2:3], v[50:51]
	v_pk_fma_f32 v[92:93], v[4:5], v[52:53], v[92:93]
	v_pk_fma_f32 v[94:95], v[6:7], v[54:55], v[94:95]
	v_add_f32_dpp v114, v114, v114 quad_perm:[1,0,3,2] row_mask:0xf bank_mask:0xf bound_ctrl:1
	v_pk_add_f32 v[92:93], v[92:93], v[94:95]
	v_pk_mul_f32 v[102:103], v[72:73], v[88:89] op_sel:[0,1] op_sel_hi:[1,1]
	v_add_f32_dpp v114, v114, v114 quad_perm:[2,3,0,1] row_mask:0xf bank_mask:0xf bound_ctrl:1
	v_add_f32_e32 v110, v92, v93
	v_pk_mul_f32 v[104:105], v[74:75], v[88:89] op_sel:[0,1] op_sel_hi:[1,1]
	v_add_f32_dpp v115, v114, v114 row_half_mirror row_mask:0xf bank_mask:0xf bound_ctrl:1
	v_pk_mul_f32 v[106:107], v[76:77], v[88:89] op_sel:[0,1] op_sel_hi:[1,1]
	v_add_f32_dpp v110, v110, v110 quad_perm:[1,0,3,2] row_mask:0xf bank_mask:0xf bound_ctrl:1
	v_pk_mul_f32 v[108:109], v[78:79], v[88:89] op_sel:[0,1] op_sel_hi:[1,1]
	v_pk_fma_f32 v[0:1], v[0:1], v[56:57], v[102:103]
	v_add_f32_dpp v110, v110, v110 quad_perm:[2,3,0,1] row_mask:0xf bank_mask:0xf bound_ctrl:1
	v_pk_fma_f32 v[2:3], v[2:3], v[58:59], v[104:105]
	v_pk_fma_f32 v[4:5], v[4:5], v[60:61], v[106:107]
	v_add_f32_dpp v112, v110, v110 row_half_mirror row_mask:0xf bank_mask:0xf bound_ctrl:1
	v_pk_fma_f32 v[6:7], v[6:7], v[62:63], v[108:109]
	v_cndmask_b32_e64 v116, v116, v115, s[62:63]
	v_pk_fma_f32 v[0:1], v[64:65], v[112:113], v[0:1] op_sel_hi:[1,0,1]
	v_pk_fma_f32 v[2:3], v[66:67], v[112:113], v[2:3] op_sel_hi:[1,0,1]
	v_pk_fma_f32 v[4:5], v[68:69], v[112:113], v[4:5] op_sel_hi:[1,0,1]
	v_pk_fma_f32 v[6:7], v[70:71], v[112:113], v[6:7] op_sel_hi:[1,0,1]
	v_pk_mul_f32 v[98:99], v[0:1], v[80:81]
	v_pk_mul_f32 v[100:101], v[2:3], v[82:83]
	v_pk_fma_f32 v[98:99], v[4:5], v[84:85], v[98:99]
	v_pk_fma_f32 v[100:101], v[6:7], v[86:87], v[100:101]
	v_pk_add_f32 v[98:99], v[98:99], v[100:101]
	v_add_f32_e32 v114, v98, v99
	s_waitcnt lgkmcnt(0)
; DEV void scan_tile(const Params& p, int l, int tile, char* smem) {
;     ...
;       const float* cb = arr + buf * 32 * 384;
;       const int vo = 320 + half * 32 + w * 8 + r8;
;       float* yw = ybuf + buf * 1024 + cg * 32 + w * 8 + r8;
;       auto ldops = [&](ScanOps& o, int sl) {
;         const f32x4* b4 = (const f32x4*)(cb + sl * 384);
;         o.nkk0 = b4[cg * 2]; o.nkk1 = b4[cg * 2 + 1];
;         o.w0 = b4[16 + cg * 2]; o.w1 = b4[16 + cg * 2 + 1];
;         o.kka0 = b4[32 + cg * 2]; o.kka1 = b4[32 + cg * 2 + 1];
;         o.kd0 = b4[48 + cg * 2]; o.kd1 = b4[48 + cg * 2 + 1];
;         o.r0 = b4[64 + cg * 2]; o.r1 = b4[64 + cg * 2 + 1];
;         o.v = cb[sl * 384 + vo];
;       };
;       float ykeep = 0.f;
;       auto step = [&](const ScanOps& o, int sl) {
;         const f32x4 sA = S0 * o.nkk0 + S1 * o.nkk1;
;         const float sa = red8((sA[0] + sA[1]) + (sA[2] + sA[3]));
;         S0 = S0 * o.w0 + (o.kka0 * sa + o.kd0 * o.v);
;         S1 = S1 * o.w1 + (o.kka1 * sa + o.kd1 * o.v);
;         const f32x4 yA = S0 * o.r0 + S1 * o.r1;
;         const float y = red8((yA[0] + yA[1]) + (yA[2] + yA[3]));
;         ykeep = (cg == (sl & 7)) ? y : ykeep;
;       };
;       ScanOps oa, ob;
;       ldops(oa, 0);
; #pragma unroll
;       for (int s8 = 0; s8 < 32; s8 += 8) {
; #pragma unroll
;         for (int q = 0; q < 8; q += 2) {
;           ldops(ob, s8 + q + 1);
;           step(oa, s8 + q);
;           ldops(oa, (s8 + q + 2) & 31);
;           step(ob, s8 + q + 1);
;         }
;         yw[s8 * 32] = ykeep;
;       }
	ds_read_b128 v[48:51], v117 offset:16896
	ds_read_b128 v[52:55], v117 offset:16912
	ds_read_b128 v[56:59], v117 offset:17152
	ds_read_b128 v[60:63], v117 offset:17168
	ds_read_b128 v[64:67], v117 offset:17408
	ds_read_b128 v[68:71], v117 offset:17424
	ds_read_b128 v[72:75], v117 offset:17664
	ds_read_b128 v[76:79], v117 offset:17680
	ds_read_b128 v[80:83], v117 offset:17920
	ds_read_b128 v[84:87], v117 offset:17936
	v_pk_mul_f32 v[92:93], v[0:1], v[8:9]
	v_pk_mul_f32 v[94:95], v[2:3], v[10:11]
	v_pk_fma_f32 v[92:93], v[4:5], v[12:13], v[92:93]
	v_pk_fma_f32 v[94:95], v[6:7], v[14:15], v[94:95]
	v_add_f32_dpp v114, v114, v114 quad_perm:[1,0,3,2] row_mask:0xf bank_mask:0xf bound_ctrl:1
	v_pk_add_f32 v[92:93], v[92:93], v[94:95]
	v_pk_mul_f32 v[102:103], v[32:33], v[90:91] op_sel_hi:[1,0]
	v_add_f32_dpp v114, v114, v114 quad_perm:[2,3,0,1] row_mask:0xf bank_mask:0xf bound_ctrl:1
	v_add_f32_e32 v110, v92, v93
	v_pk_mul_f32 v[104:105], v[34:35], v[90:91] op_sel_hi:[1,0]
	v_add_f32_dpp v115, v114, v114 row_half_mirror row_mask:0xf bank_mask:0xf bound_ctrl:1
	v_pk_mul_f32 v[106:107], v[36:37], v[90:91] op_sel_hi:[1,0]
	v_add_f32_dpp v110, v110, v110 quad_perm:[1,0,3,2] row_mask:0xf bank_mask:0xf bound_ctrl:1
	v_pk_mul_f32 v[108:109], v[38:39], v[90:91] op_sel_hi:[1,0]
	v_pk_fma_f32 v[0:1], v[0:1], v[16:17], v[102:103]
	v_add_f32_dpp v110, v110, v110 quad_perm:[2,3,0,1] row_mask:0xf bank_mask:0xf bound_ctrl:1
	v_pk_fma_f32 v[2:3], v[2:3], v[18:19], v[104:105]
	v_pk_fma_f32 v[4:5], v[4:5], v[20:21], v[106:107]
	v_add_f32_dpp v112, v110, v110 row_half_mirror row_mask:0xf bank_mask:0xf bound_ctrl:1
	v_pk_fma_f32 v[6:7], v[6:7], v[22:23], v[108:109]
	v_cndmask_b32_e64 v116, v116, v115, s[64:65]
	v_pk_fma_f32 v[0:1], v[24:25], v[112:113], v[0:1] op_sel_hi:[1,0,1]
	v_pk_fma_f32 v[2:3], v[26:27], v[112:113], v[2:3] op_sel_hi:[1,0,1]
	v_pk_fma_f32 v[4:5], v[28:29], v[112:113], v[4:5] op_sel_hi:[1,0,1]
	v_pk_fma_f32 v[6:7], v[30:31], v[112:113], v[6:7] op_sel_hi:[1,0,1]
	v_pk_mul_f32 v[98:99], v[0:1], v[40:41]
	v_pk_mul_f32 v[100:101], v[2:3], v[42:43]
	v_pk_fma_f32 v[98:99], v[4:5], v[44:45], v[98:99]
	v_pk_fma_f32 v[100:101], v[6:7], v[46:47], v[100:101]
	v_pk_add_f32 v[98:99], v[98:99], v[100:101]
	v_add_f32_e32 v114, v98, v99
	s_waitcnt lgkmcnt(0)
	ds_read_b128 v[8:11], v117 offset:18432
	ds_read_b128 v[12:15], v117 offset:18448
	ds_read_b128 v[16:19], v117 offset:18688
	ds_read_b128 v[20:23], v117 offset:18704
	ds_read_b128 v[24:27], v117 offset:18944
	ds_read_b128 v[28:31], v117 offset:18960
	ds_read_b128 v[32:35], v117 offset:19200
	ds_read_b128 v[36:39], v117 offset:19216
	ds_read_b128 v[40:43], v117 offset:19456
	ds_read_b128 v[44:47], v117 offset:19472
	ds_read2st64_b32 v[88:89], v118 offset0:77 offset1:83
	v_pk_mul_f32 v[92:93], v[0:1], v[48:49]
	v_pk_mul_f32 v[94:95], v[2:3], v[50:51]
	v_pk_fma_f32 v[92:93], v[4:5], v[52:53], v[92:93]
	v_pk_fma_f32 v[94:95], v[6:7], v[54:55], v[94:95]
	v_add_f32_dpp v114, v114, v114 quad_perm:[1,0,3,2] row_mask:0xf bank_mask:0xf bound_ctrl:1
	v_pk_add_f32 v[92:93], v[92:93], v[94:95]
	v_pk_mul_f32 v[102:103], v[72:73], v[90:91] op_sel:[0,1] op_sel_hi:[1,1]
	v_add_f32_dpp v114, v114, v114 quad_perm:[2,3,0,1] row_mask:0xf bank_mask:0xf bound_ctrl:1
	v_add_f32_e32 v110, v92, v93
	v_pk_mul_f32 v[104:105], v[74:75], v[90:91] op_sel:[0,1] op_sel_hi:[1,1]
	v_add_f32_dpp v115, v114, v114 row_half_mirror row_mask:0xf bank_mask:0xf bound_ctrl:1
	v_pk_mul_f32 v[106:107], v[76:77], v[90:91] op_sel:[0,1] op_sel_hi:[1,1]
	v_add_f32_dpp v110, v110, v110 quad_perm:[1,0,3,2] row_mask:0xf bank_mask:0xf bound_ctrl:1
	v_pk_mul_f32 v[108:109], v[78:79], v[90:91] op_sel:[0,1] op_sel_hi:[1,1]
	v_pk_fma_f32 v[0:1], v[0:1], v[56:57], v[102:103]
	v_add_f32_dpp v110, v110, v110 quad_perm:[2,3,0,1] row_mask:0xf bank_mask:0xf bound_ctrl:1
	v_pk_fma_f32 v[2:3], v[2:3], v[58:59], v[104:105]
	v_pk_fma_f32 v[4:5], v[4:5], v[60:61], v[106:107]
	v_add_f32_dpp v112, v110, v110 row_half_mirror row_mask:0xf bank_mask:0xf bound_ctrl:1
	v_pk_fma_f32 v[6:7], v[6:7], v[62:63], v[108:109]
	v_cndmask_b32_e64 v116, v116, v115, s[66:67]
	v_pk_fma_f32 v[0:1], v[64:65], v[112:113], v[0:1] op_sel_hi:[1,0,1]
	v_pk_fma_f32 v[2:3], v[66:67], v[112:113], v[2:3] op_sel_hi:[1,0,1]
	v_pk_fma_f32 v[4:5], v[68:69], v[112:113], v[4:5] op_sel_hi:[1,0,1]
	v_pk_fma_f32 v[6:7], v[70:71], v[112:113], v[6:7] op_sel_hi:[1,0,1]
	v_pk_mul_f32 v[98:99], v[0:1], v[80:81]
	v_pk_mul_f32 v[100:101], v[2:3], v[82:83]
	v_pk_fma_f32 v[98:99], v[4:5], v[84:85], v[98:99]
	v_pk_fma_f32 v[100:101], v[6:7], v[86:87], v[100:101]
	v_pk_add_f32 v[98:99], v[98:99], v[100:101]
	v_add_f32_e32 v114, v98, v99
	s_waitcnt lgkmcnt(0)
; DEV void scan_tile(const Params& p, int l, int tile, char* smem) {
;     ...
;       const float* cb = arr + buf * 32 * 384;
;       const int vo = 320 + half * 32 + w * 8 + r8;
;       float* yw = ybuf + buf * 1024 + cg * 32 + w * 8 + r8;
;       auto ldops = [&](ScanOps& o, int sl) {
;         const f32x4* b4 = (const f32x4*)(cb + sl * 384);
;         o.nkk0 = b4[cg * 2]; o.nkk1 = b4[cg * 2 + 1];
;         o.w0 = b4[16 + cg * 2]; o.w1 = b4[16 + cg * 2 + 1];
;         o.kka0 = b4[32 + cg * 2]; o.kka1 = b4[32 + cg * 2 + 1];
;         o.kd0 = b4[48 + cg * 2]; o.kd1 = b4[48 + cg * 2 + 1];
;         o.r0 = b4[64 + cg * 2]; o.r1 = b4[64 + cg * 2 + 1];
;         o.v = cb[sl * 384 + vo];
;       };
;       float ykeep = 0.f;
;       auto step = [&](const ScanOps& o, int sl) {
;         const f32x4 sA = S0 * o.nkk0 + S1 * o.nkk1;
;         const float sa = red8((sA[0] + sA[1]) + (sA[2] + sA[3]));
;         S0 = S0 * o.w0 + (o.kka0 * sa + o.kd0 * o.v);
;         S1 = S1 * o.w1 + (o.kka1 * sa + o.kd1 * o.v);
;         const f32x4 yA = S0 * o.r0 + S1 * o.r1;
;         const float y = red8((yA[0] + yA[1]) + (yA[2] + yA[3]));
;         ykeep = (cg == (sl & 7)) ? y : ykeep;
;       };
;       ScanOps oa, ob;
;       ldops(oa, 0);
; #pragma unroll
;       for (int s8 = 0; s8 < 32; s8 += 8) {
; #pragma unroll
;         for (int q = 0; q < 8; q += 2) {
;           ldops(ob, s8 + q + 1);
;           step(oa, s8 + q);
;           ldops(oa, (s8 + q + 2) & 31);
;           step(ob, s8 + q + 1);
;         }
;         yw[s8 * 32] = ykeep;
;       }
	ds_read_b128 v[48:51], v117 offset:19968
	ds_read_b128 v[52:55], v117 offset:19984
	ds_read_b128 v[56:59], v117 offset:20224
	ds_read_b128 v[60:63], v117 offset:20240
	ds_read_b128 v[64:67], v117 offset:20480
	ds_read_b128 v[68:71], v117 offset:20496
	ds_read_b128 v[72:75], v117 offset:20736
	ds_read_b128 v[76:79], v117 offset:20752
	ds_read_b128 v[80:83], v117 offset:20992
	ds_read_b128 v[84:87], v117 offset:21008
	v_pk_mul_f32 v[92:93], v[0:1], v[8:9]
	v_pk_mul_f32 v[94:95], v[2:3], v[10:11]
	v_pk_fma_f32 v[92:93], v[4:5], v[12:13], v[92:93]
	v_pk_fma_f32 v[94:95], v[6:7], v[14:15], v[94:95]
	v_add_f32_dpp v114, v114, v114 quad_perm:[1,0,3,2] row_mask:0xf bank_mask:0xf bound_ctrl:1
	v_pk_add_f32 v[92:93], v[92:93], v[94:95]
	v_pk_mul_f32 v[102:103], v[32:33], v[88:89] op_sel_hi:[1,0]
	v_add_f32_dpp v114, v114, v114 quad_perm:[2,3,0,1] row_mask:0xf bank_mask:0xf bound_ctrl:1
	v_add_f32_e32 v110, v92, v93
	v_pk_mul_f32 v[104:105], v[34:35], v[88:89] op_sel_hi:[1,0]
	v_add_f32_dpp v115, v114, v114 row_half_mirror row_mask:0xf bank_mask:0xf bound_ctrl:1
	v_pk_mul_f32 v[106:107], v[36:37], v[88:89] op_sel_hi:[1,0]
	v_add_f32_dpp v110, v110, v110 quad_perm:[1,0,3,2] row_mask:0xf bank_mask:0xf bound_ctrl:1
	v_pk_mul_f32 v[108:109], v[38:39], v[88:89] op_sel_hi:[1,0]
	v_pk_fma_f32 v[0:1], v[0:1], v[16:17], v[102:103]
	v_add_f32_dpp v110, v110, v110 quad_perm:[2,3,0,1] row_mask:0xf bank_mask:0xf bound_ctrl:1
	v_pk_fma_f32 v[2:3], v[2:3], v[18:19], v[104:105]
	v_pk_fma_f32 v[4:5], v[4:5], v[20:21], v[106:107]
	v_add_f32_dpp v112, v110, v110 row_half_mirror row_mask:0xf bank_mask:0xf bound_ctrl:1
	v_pk_fma_f32 v[6:7], v[6:7], v[22:23], v[108:109]
	v_cndmask_b32_e64 v116, v116, v115, s[68:69]
	v_pk_fma_f32 v[0:1], v[24:25], v[112:113], v[0:1] op_sel_hi:[1,0,1]
	v_pk_fma_f32 v[2:3], v[26:27], v[112:113], v[2:3] op_sel_hi:[1,0,1]
	v_pk_fma_f32 v[4:5], v[28:29], v[112:113], v[4:5] op_sel_hi:[1,0,1]
	v_pk_fma_f32 v[6:7], v[30:31], v[112:113], v[6:7] op_sel_hi:[1,0,1]
	v_pk_mul_f32 v[98:99], v[0:1], v[40:41]
	v_pk_mul_f32 v[100:101], v[2:3], v[42:43]
	v_pk_fma_f32 v[98:99], v[4:5], v[44:45], v[98:99]
	v_pk_fma_f32 v[100:101], v[6:7], v[46:47], v[100:101]
	v_pk_add_f32 v[98:99], v[98:99], v[100:101]
	v_add_f32_e32 v114, v98, v99
	s_waitcnt lgkmcnt(0)
	ds_read_b128 v[8:11], v117 offset:21504
	ds_read_b128 v[12:15], v117 offset:21520
	ds_read_b128 v[16:19], v117 offset:21760
	ds_read_b128 v[20:23], v117 offset:21776
	ds_read_b128 v[24:27], v117 offset:22016
	ds_read_b128 v[28:31], v117 offset:22032
	ds_read_b128 v[32:35], v117 offset:22272
	ds_read_b128 v[36:39], v117 offset:22288
	ds_read_b128 v[40:43], v117 offset:22528
	ds_read_b128 v[44:47], v117 offset:22544
	ds_read2st64_b32 v[90:91], v118 offset0:89 offset1:95
	v_pk_mul_f32 v[92:93], v[0:1], v[48:49]
	v_pk_mul_f32 v[94:95], v[2:3], v[50:51]
	v_pk_fma_f32 v[92:93], v[4:5], v[52:53], v[92:93]
	v_pk_fma_f32 v[94:95], v[6:7], v[54:55], v[94:95]
	v_add_f32_dpp v114, v114, v114 quad_perm:[1,0,3,2] row_mask:0xf bank_mask:0xf bound_ctrl:1
	v_pk_add_f32 v[92:93], v[92:93], v[94:95]
	v_pk_mul_f32 v[102:103], v[72:73], v[88:89] op_sel:[0,1] op_sel_hi:[1,1]
	v_add_f32_dpp v114, v114, v114 quad_perm:[2,3,0,1] row_mask:0xf bank_mask:0xf bound_ctrl:1
	v_add_f32_e32 v110, v92, v93
	v_pk_mul_f32 v[104:105], v[74:75], v[88:89] op_sel:[0,1] op_sel_hi:[1,1]
	v_add_f32_dpp v115, v114, v114 row_half_mirror row_mask:0xf bank_mask:0xf bound_ctrl:1
	v_pk_mul_f32 v[106:107], v[76:77], v[88:89] op_sel:[0,1] op_sel_hi:[1,1]
	v_add_f32_dpp v110, v110, v110 quad_perm:[1,0,3,2] row_mask:0xf bank_mask:0xf bound_ctrl:1
	v_pk_mul_f32 v[108:109], v[78:79], v[88:89] op_sel:[0,1] op_sel_hi:[1,1]
	v_pk_fma_f32 v[0:1], v[0:1], v[56:57], v[102:103]
	v_add_f32_dpp v110, v110, v110 quad_perm:[2,3,0,1] row_mask:0xf bank_mask:0xf bound_ctrl:1
	v_pk_fma_f32 v[2:3], v[2:3], v[58:59], v[104:105]
	v_pk_fma_f32 v[4:5], v[4:5], v[60:61], v[106:107]
	v_add_f32_dpp v112, v110, v110 row_half_mirror row_mask:0xf bank_mask:0xf bound_ctrl:1
	v_pk_fma_f32 v[6:7], v[6:7], v[62:63], v[108:109]
	v_cndmask_b32_e64 v116, v116, v115, s[70:71]
	v_pk_fma_f32 v[0:1], v[64:65], v[112:113], v[0:1] op_sel_hi:[1,0,1]
	v_pk_fma_f32 v[2:3], v[66:67], v[112:113], v[2:3] op_sel_hi:[1,0,1]
	v_pk_fma_f32 v[4:5], v[68:69], v[112:113], v[4:5] op_sel_hi:[1,0,1]
	v_pk_fma_f32 v[6:7], v[70:71], v[112:113], v[6:7] op_sel_hi:[1,0,1]
	v_pk_mul_f32 v[98:99], v[0:1], v[80:81]
	v_pk_mul_f32 v[100:101], v[2:3], v[82:83]
	v_pk_fma_f32 v[98:99], v[4:5], v[84:85], v[98:99]
	v_pk_fma_f32 v[100:101], v[6:7], v[86:87], v[100:101]
	v_pk_add_f32 v[98:99], v[98:99], v[100:101]
	v_add_f32_e32 v114, v98, v99
	s_waitcnt lgkmcnt(0)
; DEV void scan_tile(const Params& p, int l, int tile, char* smem) {
;     ...
;       const float* cb = arr + buf * 32 * 384;
;       const int vo = 320 + half * 32 + w * 8 + r8;
;       float* yw = ybuf + buf * 1024 + cg * 32 + w * 8 + r8;
;       auto ldops = [&](ScanOps& o, int sl) {
;         const f32x4* b4 = (const f32x4*)(cb + sl * 384);
;         o.nkk0 = b4[cg * 2]; o.nkk1 = b4[cg * 2 + 1];
;         o.w0 = b4[16 + cg * 2]; o.w1 = b4[16 + cg * 2 + 1];
;         o.kka0 = b4[32 + cg * 2]; o.kka1 = b4[32 + cg * 2 + 1];
;         o.kd0 = b4[48 + cg * 2]; o.kd1 = b4[48 + cg * 2 + 1];
;         o.r0 = b4[64 + cg * 2]; o.r1 = b4[64 + cg * 2 + 1];
;         o.v = cb[sl * 384 + vo];
;       };
;       float ykeep = 0.f;
;       auto step = [&](const ScanOps& o, int sl) {
;         const f32x4 sA = S0 * o.nkk0 + S1 * o.nkk1;
;         const float sa = red8((sA[0] + sA[1]) + (sA[2] + sA[3]));
;         S0 = S0 * o.w0 + (o.kka0 * sa + o.kd0 * o.v);
;         S1 = S1 * o.w1 + (o.kka1 * sa + o.kd1 * o.v);
;         const f32x4 yA = S0 * o.r0 + S1 * o.r1;
;         const float y = red8((yA[0] + yA[1]) + (yA[2] + yA[3]));
;         ykeep = (cg == (sl & 7)) ? y : ykeep;
;       };
;       ScanOps oa, ob;
;       ldops(oa, 0);
; #pragma unroll
;       for (int s8 = 0; s8 < 32; s8 += 8) {
; #pragma unroll
;         for (int q = 0; q < 8; q += 2) {
;           ldops(ob, s8 + q + 1);
;           step(oa, s8 + q);
;           ldops(oa, (s8 + q + 2) & 31);
;           step(ob, s8 + q + 1);
;         }
;         yw[s8 * 32] = ykeep;
;       }
	ds_read_b128 v[48:51], v117 offset:23040
	ds_read_b128 v[52:55], v117 offset:23056
	ds_read_b128 v[56:59], v117 offset:23296
	ds_read_b128 v[60:63], v117 offset:23312
	ds_read_b128 v[64:67], v117 offset:23552
	ds_read_b128 v[68:71], v117 offset:23568
	ds_read_b128 v[72:75], v117 offset:23808
	ds_read_b128 v[76:79], v117 offset:23824
	ds_read_b128 v[80:83], v117 offset:24064
	ds_read_b128 v[84:87], v117 offset:24080
	v_pk_mul_f32 v[92:93], v[0:1], v[8:9]
	v_pk_mul_f32 v[94:95], v[2:3], v[10:11]
	v_pk_fma_f32 v[92:93], v[4:5], v[12:13], v[92:93]
	v_pk_fma_f32 v[94:95], v[6:7], v[14:15], v[94:95]
	v_add_f32_dpp v114, v114, v114 quad_perm:[1,0,3,2] row_mask:0xf bank_mask:0xf bound_ctrl:1
	v_pk_add_f32 v[92:93], v[92:93], v[94:95]
	v_pk_mul_f32 v[102:103], v[32:33], v[90:91] op_sel_hi:[1,0]
	v_add_f32_dpp v114, v114, v114 quad_perm:[2,3,0,1] row_mask:0xf bank_mask:0xf bound_ctrl:1
	v_add_f32_e32 v110, v92, v93
	v_pk_mul_f32 v[104:105], v[34:35], v[90:91] op_sel_hi:[1,0]
	v_add_f32_dpp v115, v114, v114 row_half_mirror row_mask:0xf bank_mask:0xf bound_ctrl:1
	v_pk_mul_f32 v[106:107], v[36:37], v[90:91] op_sel_hi:[1,0]
	v_add_f32_dpp v110, v110, v110 quad_perm:[1,0,3,2] row_mask:0xf bank_mask:0xf bound_ctrl:1
	v_pk_mul_f32 v[108:109], v[38:39], v[90:91] op_sel_hi:[1,0]
	v_pk_fma_f32 v[0:1], v[0:1], v[16:17], v[102:103]
	v_add_f32_dpp v110, v110, v110 quad_perm:[2,3,0,1] row_mask:0xf bank_mask:0xf bound_ctrl:1
	v_pk_fma_f32 v[2:3], v[2:3], v[18:19], v[104:105]
	v_pk_fma_f32 v[4:5], v[4:5], v[20:21], v[106:107]
	v_add_f32_dpp v112, v110, v110 row_half_mirror row_mask:0xf bank_mask:0xf bound_ctrl:1
	v_pk_fma_f32 v[6:7], v[6:7], v[22:23], v[108:109]
	v_cndmask_b32_e64 v116, v116, v115, s[0:1]
	v_pk_fma_f32 v[0:1], v[24:25], v[112:113], v[0:1] op_sel_hi:[1,0,1]
	v_pk_fma_f32 v[2:3], v[26:27], v[112:113], v[2:3] op_sel_hi:[1,0,1]
	v_pk_fma_f32 v[4:5], v[28:29], v[112:113], v[4:5] op_sel_hi:[1,0,1]
	v_pk_fma_f32 v[6:7], v[30:31], v[112:113], v[6:7] op_sel_hi:[1,0,1]
	v_pk_mul_f32 v[98:99], v[0:1], v[40:41]
	v_pk_mul_f32 v[100:101], v[2:3], v[42:43]
	v_pk_fma_f32 v[98:99], v[4:5], v[44:45], v[98:99]
	v_pk_fma_f32 v[100:101], v[6:7], v[46:47], v[100:101]
	v_pk_add_f32 v[98:99], v[98:99], v[100:101]
	v_add_f32_e32 v114, v98, v99
	s_waitcnt lgkmcnt(0)
	ds_read_b128 v[8:11], v117 offset:24576
	ds_read_b128 v[12:15], v117 offset:24592
	ds_read_b128 v[16:19], v117 offset:24832
	ds_read_b128 v[20:23], v117 offset:24848
	ds_read_b128 v[24:27], v117 offset:25088
	ds_read_b128 v[28:31], v117 offset:25104
	ds_read_b128 v[32:35], v117 offset:25344
	ds_read_b128 v[36:39], v117 offset:25360
	ds_read_b128 v[40:43], v117 offset:25600
	ds_read_b128 v[44:47], v117 offset:25616
	ds_read2st64_b32 v[88:89], v118 offset0:101 offset1:107
	v_pk_mul_f32 v[92:93], v[0:1], v[48:49]
	v_pk_mul_f32 v[94:95], v[2:3], v[50:51]
	v_pk_fma_f32 v[92:93], v[4:5], v[52:53], v[92:93]
	v_pk_fma_f32 v[94:95], v[6:7], v[54:55], v[94:95]
	v_add_f32_dpp v114, v114, v114 quad_perm:[1,0,3,2] row_mask:0xf bank_mask:0xf bound_ctrl:1
	v_pk_add_f32 v[92:93], v[92:93], v[94:95]
	v_pk_mul_f32 v[102:103], v[72:73], v[90:91] op_sel:[0,1] op_sel_hi:[1,1]
	v_add_f32_dpp v114, v114, v114 quad_perm:[2,3,0,1] row_mask:0xf bank_mask:0xf bound_ctrl:1
	v_add_f32_e32 v110, v92, v93
	v_pk_mul_f32 v[104:105], v[74:75], v[90:91] op_sel:[0,1] op_sel_hi:[1,1]
	v_add_f32_dpp v115, v114, v114 row_half_mirror row_mask:0xf bank_mask:0xf bound_ctrl:1
	v_pk_mul_f32 v[106:107], v[76:77], v[90:91] op_sel:[0,1] op_sel_hi:[1,1]
	v_add_f32_dpp v110, v110, v110 quad_perm:[1,0,3,2] row_mask:0xf bank_mask:0xf bound_ctrl:1
	v_pk_mul_f32 v[108:109], v[78:79], v[90:91] op_sel:[0,1] op_sel_hi:[1,1]
	v_pk_fma_f32 v[0:1], v[0:1], v[56:57], v[102:103]
	v_add_f32_dpp v110, v110, v110 quad_perm:[2,3,0,1] row_mask:0xf bank_mask:0xf bound_ctrl:1
	v_pk_fma_f32 v[2:3], v[2:3], v[58:59], v[104:105]
	v_pk_fma_f32 v[4:5], v[4:5], v[60:61], v[106:107]
	v_add_f32_dpp v112, v110, v110 row_half_mirror row_mask:0xf bank_mask:0xf bound_ctrl:1
	v_pk_fma_f32 v[6:7], v[6:7], v[62:63], v[108:109]
	v_cndmask_b32_e64 v116, v116, v115, s[96:97]
	v_pk_fma_f32 v[0:1], v[64:65], v[112:113], v[0:1] op_sel_hi:[1,0,1]
	v_pk_fma_f32 v[2:3], v[66:67], v[112:113], v[2:3] op_sel_hi:[1,0,1]
	v_pk_fma_f32 v[4:5], v[68:69], v[112:113], v[4:5] op_sel_hi:[1,0,1]
	v_pk_fma_f32 v[6:7], v[70:71], v[112:113], v[6:7] op_sel_hi:[1,0,1]
	v_pk_mul_f32 v[98:99], v[0:1], v[80:81]
	v_pk_mul_f32 v[100:101], v[2:3], v[82:83]
	v_pk_fma_f32 v[98:99], v[4:5], v[84:85], v[98:99]
	v_pk_fma_f32 v[100:101], v[6:7], v[86:87], v[100:101]
	v_pk_add_f32 v[98:99], v[98:99], v[100:101]
	v_add_f32_e32 v114, v98, v99
	s_waitcnt lgkmcnt(0)
; DEV void scan_tile(const Params& p, int l, int tile, char* smem) {
;     ...
;       const float* cb = arr + buf * 32 * 384;
;       const int vo = 320 + half * 32 + w * 8 + r8;
;       float* yw = ybuf + buf * 1024 + cg * 32 + w * 8 + r8;
;       auto ldops = [&](ScanOps& o, int sl) {
;         const f32x4* b4 = (const f32x4*)(cb + sl * 384);
;         o.nkk0 = b4[cg * 2]; o.nkk1 = b4[cg * 2 + 1];
;         o.w0 = b4[16 + cg * 2]; o.w1 = b4[16 + cg * 2 + 1];
;         o.kka0 = b4[32 + cg * 2]; o.kka1 = b4[32 + cg * 2 + 1];
;         o.kd0 = b4[48 + cg * 2]; o.kd1 = b4[48 + cg * 2 + 1];
;         o.r0 = b4[64 + cg * 2]; o.r1 = b4[64 + cg * 2 + 1];
;         o.v = cb[sl * 384 + vo];
;       };
;       float ykeep = 0.f;
;       auto step = [&](const ScanOps& o, int sl) {
;         const f32x4 sA = S0 * o.nkk0 + S1 * o.nkk1;
;         const float sa = red8((sA[0] + sA[1]) + (sA[2] + sA[3]));
;         S0 = S0 * o.w0 + (o.kka0 * sa + o.kd0 * o.v);
;         S1 = S1 * o.w1 + (o.kka1 * sa + o.kd1 * o.v);
;         const f32x4 yA = S0 * o.r0 + S1 * o.r1;
;         const float y = red8((yA[0] + yA[1]) + (yA[2] + yA[3]));
;         ykeep = (cg == (sl & 7)) ? y : ykeep;
;       };
;       ScanOps oa, ob;
;       ldops(oa, 0);
; #pragma unroll
;       for (int s8 = 0; s8 < 32; s8 += 8) {
; #pragma unroll
;         for (int q = 0; q < 8; q += 2) {
;           ldops(ob, s8 + q + 1);
;           step(oa, s8 + q);
;           ldops(oa, (s8 + q + 2) & 31);
;           step(ob, s8 + q + 1);
;         }
;         yw[s8 * 32] = ykeep;
;       }
	ds_read_b128 v[48:51], v117 offset:26112
	ds_read_b128 v[52:55], v117 offset:26128
	ds_read_b128 v[56:59], v117 offset:26368
	ds_read_b128 v[60:63], v117 offset:26384
	ds_read_b128 v[64:67], v117 offset:26624
	ds_read_b128 v[68:71], v117 offset:26640
	ds_read_b128 v[72:75], v117 offset:26880
	ds_read_b128 v[76:79], v117 offset:26896
	ds_read_b128 v[80:83], v117 offset:27136
	ds_read_b128 v[84:87], v117 offset:27152
	v_pk_mul_f32 v[92:93], v[0:1], v[8:9]
	v_pk_mul_f32 v[94:95], v[2:3], v[10:11]
	v_pk_fma_f32 v[92:93], v[4:5], v[12:13], v[92:93]
	v_pk_fma_f32 v[94:95], v[6:7], v[14:15], v[94:95]
	v_add_f32_dpp v114, v114, v114 quad_perm:[1,0,3,2] row_mask:0xf bank_mask:0xf bound_ctrl:1
	v_pk_add_f32 v[92:93], v[92:93], v[94:95]
	v_pk_mul_f32 v[102:103], v[32:33], v[88:89] op_sel_hi:[1,0]
	v_add_f32_dpp v114, v114, v114 quad_perm:[2,3,0,1] row_mask:0xf bank_mask:0xf bound_ctrl:1
	v_add_f32_e32 v110, v92, v93
	v_pk_mul_f32 v[104:105], v[34:35], v[88:89] op_sel_hi:[1,0]
	v_add_f32_dpp v115, v114, v114 row_half_mirror row_mask:0xf bank_mask:0xf bound_ctrl:1
	v_pk_mul_f32 v[106:107], v[36:37], v[88:89] op_sel_hi:[1,0]
	v_add_f32_dpp v110, v110, v110 quad_perm:[1,0,3,2] row_mask:0xf bank_mask:0xf bound_ctrl:1
	v_pk_mul_f32 v[108:109], v[38:39], v[88:89] op_sel_hi:[1,0]
	v_pk_fma_f32 v[0:1], v[0:1], v[16:17], v[102:103]
	v_add_f32_dpp v110, v110, v110 quad_perm:[2,3,0,1] row_mask:0xf bank_mask:0xf bound_ctrl:1
	v_pk_fma_f32 v[2:3], v[2:3], v[18:19], v[104:105]
	v_pk_fma_f32 v[4:5], v[4:5], v[20:21], v[106:107]
	v_add_f32_dpp v112, v110, v110 row_half_mirror row_mask:0xf bank_mask:0xf bound_ctrl:1
	v_pk_fma_f32 v[6:7], v[6:7], v[22:23], v[108:109]
	v_cndmask_b32_e64 v116, v116, v115, vcc
	ds_write_b32 v119, v116 offset:1024
	v_pk_fma_f32 v[0:1], v[24:25], v[112:113], v[0:1] op_sel_hi:[1,0,1]
	v_pk_fma_f32 v[2:3], v[26:27], v[112:113], v[2:3] op_sel_hi:[1,0,1]
	v_pk_fma_f32 v[4:5], v[28:29], v[112:113], v[4:5] op_sel_hi:[1,0,1]
	v_pk_fma_f32 v[6:7], v[30:31], v[112:113], v[6:7] op_sel_hi:[1,0,1]
	v_pk_mul_f32 v[98:99], v[0:1], v[40:41]
	v_pk_mul_f32 v[100:101], v[2:3], v[42:43]
	v_pk_fma_f32 v[98:99], v[4:5], v[44:45], v[98:99]
	v_pk_fma_f32 v[100:101], v[6:7], v[46:47], v[100:101]
	v_pk_add_f32 v[98:99], v[98:99], v[100:101]
	v_add_f32_e32 v114, v98, v99
	s_waitcnt lgkmcnt(1)
	ds_read_b128 v[8:11], v117 offset:27648
	ds_read_b128 v[12:15], v117 offset:27664
	ds_read_b128 v[16:19], v117 offset:27904
	ds_read_b128 v[20:23], v117 offset:27920
	ds_read_b128 v[24:27], v117 offset:28160
	ds_read_b128 v[28:31], v117 offset:28176
	ds_read_b128 v[32:35], v117 offset:28416
	ds_read_b128 v[36:39], v117 offset:28432
	ds_read_b128 v[40:43], v117 offset:28672
	ds_read_b128 v[44:47], v117 offset:28688
	ds_read2st64_b32 v[90:91], v118 offset0:113 offset1:119
	v_pk_mul_f32 v[92:93], v[0:1], v[48:49]
	v_pk_mul_f32 v[94:95], v[2:3], v[50:51]
	v_pk_fma_f32 v[92:93], v[4:5], v[52:53], v[92:93]
	v_pk_fma_f32 v[94:95], v[6:7], v[54:55], v[94:95]
	v_add_f32_dpp v114, v114, v114 quad_perm:[1,0,3,2] row_mask:0xf bank_mask:0xf bound_ctrl:1
	v_pk_add_f32 v[92:93], v[92:93], v[94:95]
	v_pk_mul_f32 v[102:103], v[72:73], v[88:89] op_sel:[0,1] op_sel_hi:[1,1]
	v_add_f32_dpp v114, v114, v114 quad_perm:[2,3,0,1] row_mask:0xf bank_mask:0xf bound_ctrl:1
	v_add_f32_e32 v110, v92, v93
	v_pk_mul_f32 v[104:105], v[74:75], v[88:89] op_sel:[0,1] op_sel_hi:[1,1]
	v_add_f32_dpp v115, v114, v114 row_half_mirror row_mask:0xf bank_mask:0xf bound_ctrl:1
	v_pk_mul_f32 v[106:107], v[76:77], v[88:89] op_sel:[0,1] op_sel_hi:[1,1]
	v_add_f32_dpp v110, v110, v110 quad_perm:[1,0,3,2] row_mask:0xf bank_mask:0xf bound_ctrl:1
	v_pk_mul_f32 v[108:109], v[78:79], v[88:89] op_sel:[0,1] op_sel_hi:[1,1]
	v_pk_fma_f32 v[0:1], v[0:1], v[56:57], v[102:103]
	v_add_f32_dpp v110, v110, v110 quad_perm:[2,3,0,1] row_mask:0xf bank_mask:0xf bound_ctrl:1
	v_pk_fma_f32 v[2:3], v[2:3], v[58:59], v[104:105]
	v_pk_fma_f32 v[4:5], v[4:5], v[60:61], v[106:107]
	v_add_f32_dpp v112, v110, v110 row_half_mirror row_mask:0xf bank_mask:0xf bound_ctrl:1
	v_pk_fma_f32 v[6:7], v[6:7], v[62:63], v[108:109]
	v_cndmask_b32_e64 v116, v116, v115, s[62:63]
	v_pk_fma_f32 v[0:1], v[64:65], v[112:113], v[0:1] op_sel_hi:[1,0,1]
	v_pk_fma_f32 v[2:3], v[66:67], v[112:113], v[2:3] op_sel_hi:[1,0,1]
	v_pk_fma_f32 v[4:5], v[68:69], v[112:113], v[4:5] op_sel_hi:[1,0,1]
	v_pk_fma_f32 v[6:7], v[70:71], v[112:113], v[6:7] op_sel_hi:[1,0,1]
	v_pk_mul_f32 v[98:99], v[0:1], v[80:81]
	v_pk_mul_f32 v[100:101], v[2:3], v[82:83]
	v_pk_fma_f32 v[98:99], v[4:5], v[84:85], v[98:99]
	v_pk_fma_f32 v[100:101], v[6:7], v[86:87], v[100:101]
	v_pk_add_f32 v[98:99], v[98:99], v[100:101]
	v_add_f32_e32 v114, v98, v99
	s_waitcnt lgkmcnt(0)
; DEV void scan_tile(const Params& p, int l, int tile, char* smem) {
;     ...
;       const float* cb = arr + buf * 32 * 384;
;       const int vo = 320 + half * 32 + w * 8 + r8;
;       float* yw = ybuf + buf * 1024 + cg * 32 + w * 8 + r8;
;       auto ldops = [&](ScanOps& o, int sl) {
;         const f32x4* b4 = (const f32x4*)(cb + sl * 384);
;         o.nkk0 = b4[cg * 2]; o.nkk1 = b4[cg * 2 + 1];
;         o.w0 = b4[16 + cg * 2]; o.w1 = b4[16 + cg * 2 + 1];
;         o.kka0 = b4[32 + cg * 2]; o.kka1 = b4[32 + cg * 2 + 1];
;         o.kd0 = b4[48 + cg * 2]; o.kd1 = b4[48 + cg * 2 + 1];
;         o.r0 = b4[64 + cg * 2]; o.r1 = b4[64 + cg * 2 + 1];
;         o.v = cb[sl * 384 + vo];
;       };
;       float ykeep = 0.f;
;       auto step = [&](const ScanOps& o, int sl) {
;         const f32x4 sA = S0 * o.nkk0 + S1 * o.nkk1;
;         const float sa = red8((sA[0] + sA[1]) + (sA[2] + sA[3]));
;         S0 = S0 * o.w0 + (o.kka0 * sa + o.kd0 * o.v);
;         S1 = S1 * o.w1 + (o.kka1 * sa + o.kd1 * o.v);
;         const f32x4 yA = S0 * o.r0 + S1 * o.r1;
;         const float y = red8((yA[0] + yA[1]) + (yA[2] + yA[3]));
;         ykeep = (cg == (sl & 7)) ? y : ykeep;
;       };
;       ScanOps oa, ob;
;       ldops(oa, 0);
; #pragma unroll
;       for (int s8 = 0; s8 < 32; s8 += 8) {
; #pragma unroll
;         for (int q = 0; q < 8; q += 2) {
;           ldops(ob, s8 + q + 1);
;           step(oa, s8 + q);
;           ldops(oa, (s8 + q + 2) & 31);
;           step(ob, s8 + q + 1);
;         }
;         yw[s8 * 32] = ykeep;
;       }
	ds_read_b128 v[48:51], v117 offset:29184
	ds_read_b128 v[52:55], v117 offset:29200
	ds_read_b128 v[56:59], v117 offset:29440
	ds_read_b128 v[60:63], v117 offset:29456
	ds_read_b128 v[64:67], v117 offset:29696
	ds_read_b128 v[68:71], v117 offset:29712
	ds_read_b128 v[72:75], v117 offset:29952
	ds_read_b128 v[76:79], v117 offset:29968
	ds_read_b128 v[80:83], v117 offset:30208
	ds_read_b128 v[84:87], v117 offset:30224
	v_pk_mul_f32 v[92:93], v[0:1], v[8:9]
	v_pk_mul_f32 v[94:95], v[2:3], v[10:11]
	v_pk_fma_f32 v[92:93], v[4:5], v[12:13], v[92:93]
	v_pk_fma_f32 v[94:95], v[6:7], v[14:15], v[94:95]
	v_add_f32_dpp v114, v114, v114 quad_perm:[1,0,3,2] row_mask:0xf bank_mask:0xf bound_ctrl:1
	v_pk_add_f32 v[92:93], v[92:93], v[94:95]
	v_pk_mul_f32 v[102:103], v[32:33], v[90:91] op_sel_hi:[1,0]
	v_add_f32_dpp v114, v114, v114 quad_perm:[2,3,0,1] row_mask:0xf bank_mask:0xf bound_ctrl:1
	v_add_f32_e32 v110, v92, v93
	v_pk_mul_f32 v[104:105], v[34:35], v[90:91] op_sel_hi:[1,0]
	v_add_f32_dpp v115, v114, v114 row_half_mirror row_mask:0xf bank_mask:0xf bound_ctrl:1
	v_pk_mul_f32 v[106:107], v[36:37], v[90:91] op_sel_hi:[1,0]
	v_add_f32_dpp v110, v110, v110 quad_perm:[1,0,3,2] row_mask:0xf bank_mask:0xf bound_ctrl:1
	v_pk_mul_f32 v[108:109], v[38:39], v[90:91] op_sel_hi:[1,0]
	v_pk_fma_f32 v[0:1], v[0:1], v[16:17], v[102:103]
	v_add_f32_dpp v110, v110, v110 quad_perm:[2,3,0,1] row_mask:0xf bank_mask:0xf bound_ctrl:1
	v_pk_fma_f32 v[2:3], v[2:3], v[18:19], v[104:105]
	v_pk_fma_f32 v[4:5], v[4:5], v[20:21], v[106:107]
	v_add_f32_dpp v112, v110, v110 row_half_mirror row_mask:0xf bank_mask:0xf bound_ctrl:1
	v_pk_fma_f32 v[6:7], v[6:7], v[22:23], v[108:109]
	v_cndmask_b32_e64 v116, v116, v115, s[64:65]
	v_pk_fma_f32 v[0:1], v[24:25], v[112:113], v[0:1] op_sel_hi:[1,0,1]
	v_pk_fma_f32 v[2:3], v[26:27], v[112:113], v[2:3] op_sel_hi:[1,0,1]
	v_pk_fma_f32 v[4:5], v[28:29], v[112:113], v[4:5] op_sel_hi:[1,0,1]
	v_pk_fma_f32 v[6:7], v[30:31], v[112:113], v[6:7] op_sel_hi:[1,0,1]
	v_pk_mul_f32 v[98:99], v[0:1], v[40:41]
	v_pk_mul_f32 v[100:101], v[2:3], v[42:43]
	v_pk_fma_f32 v[98:99], v[4:5], v[44:45], v[98:99]
	v_pk_fma_f32 v[100:101], v[6:7], v[46:47], v[100:101]
	v_pk_add_f32 v[98:99], v[98:99], v[100:101]
	v_add_f32_e32 v114, v98, v99
	s_waitcnt lgkmcnt(0)
	ds_read_b128 v[8:11], v117 offset:30720
	ds_read_b128 v[12:15], v117 offset:30736
	ds_read_b128 v[16:19], v117 offset:30976
	ds_read_b128 v[20:23], v117 offset:30992
	ds_read_b128 v[24:27], v117 offset:31232
	ds_read_b128 v[28:31], v117 offset:31248
	ds_read_b128 v[32:35], v117 offset:31488
	ds_read_b128 v[36:39], v117 offset:31504
	ds_read_b128 v[40:43], v117 offset:31744
	ds_read_b128 v[44:47], v117 offset:31760
	ds_read2st64_b32 v[88:89], v118 offset0:125 offset1:131
	v_pk_mul_f32 v[92:93], v[0:1], v[48:49]
	v_pk_mul_f32 v[94:95], v[2:3], v[50:51]
	v_pk_fma_f32 v[92:93], v[4:5], v[52:53], v[92:93]
	v_pk_fma_f32 v[94:95], v[6:7], v[54:55], v[94:95]
	v_add_f32_dpp v114, v114, v114 quad_perm:[1,0,3,2] row_mask:0xf bank_mask:0xf bound_ctrl:1
	v_pk_add_f32 v[92:93], v[92:93], v[94:95]
	v_pk_mul_f32 v[102:103], v[72:73], v[90:91] op_sel:[0,1] op_sel_hi:[1,1]
	v_add_f32_dpp v114, v114, v114 quad_perm:[2,3,0,1] row_mask:0xf bank_mask:0xf bound_ctrl:1
	v_add_f32_e32 v110, v92, v93
	v_pk_mul_f32 v[104:105], v[74:75], v[90:91] op_sel:[0,1] op_sel_hi:[1,1]
	v_add_f32_dpp v115, v114, v114 row_half_mirror row_mask:0xf bank_mask:0xf bound_ctrl:1
	v_pk_mul_f32 v[106:107], v[76:77], v[90:91] op_sel:[0,1] op_sel_hi:[1,1]
	v_add_f32_dpp v110, v110, v110 quad_perm:[1,0,3,2] row_mask:0xf bank_mask:0xf bound_ctrl:1
	v_pk_mul_f32 v[108:109], v[78:79], v[90:91] op_sel:[0,1] op_sel_hi:[1,1]
	v_pk_fma_f32 v[0:1], v[0:1], v[56:57], v[102:103]
	v_add_f32_dpp v110, v110, v110 quad_perm:[2,3,0,1] row_mask:0xf bank_mask:0xf bound_ctrl:1
	v_pk_fma_f32 v[2:3], v[2:3], v[58:59], v[104:105]
	v_pk_fma_f32 v[4:5], v[4:5], v[60:61], v[106:107]
	v_add_f32_dpp v112, v110, v110 row_half_mirror row_mask:0xf bank_mask:0xf bound_ctrl:1
	v_pk_fma_f32 v[6:7], v[6:7], v[62:63], v[108:109]
	v_cndmask_b32_e64 v116, v116, v115, s[66:67]
	v_pk_fma_f32 v[0:1], v[64:65], v[112:113], v[0:1] op_sel_hi:[1,0,1]
	v_pk_fma_f32 v[2:3], v[66:67], v[112:113], v[2:3] op_sel_hi:[1,0,1]
	v_pk_fma_f32 v[4:5], v[68:69], v[112:113], v[4:5] op_sel_hi:[1,0,1]
	v_pk_fma_f32 v[6:7], v[70:71], v[112:113], v[6:7] op_sel_hi:[1,0,1]
	v_pk_mul_f32 v[98:99], v[0:1], v[80:81]
	v_pk_mul_f32 v[100:101], v[2:3], v[82:83]
	v_pk_fma_f32 v[98:99], v[4:5], v[84:85], v[98:99]
	v_pk_fma_f32 v[100:101], v[6:7], v[86:87], v[100:101]
	v_pk_add_f32 v[98:99], v[98:99], v[100:101]
	v_add_f32_e32 v114, v98, v99
	s_waitcnt lgkmcnt(0)
; DEV void scan_tile(const Params& p, int l, int tile, char* smem) {
;     ...
;       const float* cb = arr + buf * 32 * 384;
;       const int vo = 320 + half * 32 + w * 8 + r8;
;       float* yw = ybuf + buf * 1024 + cg * 32 + w * 8 + r8;
;       auto ldops = [&](ScanOps& o, int sl) {
;         const f32x4* b4 = (const f32x4*)(cb + sl * 384);
;         o.nkk0 = b4[cg * 2]; o.nkk1 = b4[cg * 2 + 1];
;         o.w0 = b4[16 + cg * 2]; o.w1 = b4[16 + cg * 2 + 1];
;         o.kka0 = b4[32 + cg * 2]; o.kka1 = b4[32 + cg * 2 + 1];
;         o.kd0 = b4[48 + cg * 2]; o.kd1 = b4[48 + cg * 2 + 1];
;         o.r0 = b4[64 + cg * 2]; o.r1 = b4[64 + cg * 2 + 1];
;         o.v = cb[sl * 384 + vo];
;       };
;       float ykeep = 0.f;
;       auto step = [&](const ScanOps& o, int sl) {
;         const f32x4 sA = S0 * o.nkk0 + S1 * o.nkk1;
;         const float sa = red8((sA[0] + sA[1]) + (sA[2] + sA[3]));
;         S0 = S0 * o.w0 + (o.kka0 * sa + o.kd0 * o.v);
;         S1 = S1 * o.w1 + (o.kka1 * sa + o.kd1 * o.v);
;         const f32x4 yA = S0 * o.r0 + S1 * o.r1;
;         const float y = red8((yA[0] + yA[1]) + (yA[2] + yA[3]));
;         ykeep = (cg == (sl & 7)) ? y : ykeep;
;       };
;       ScanOps oa, ob;
;       ldops(oa, 0);
; #pragma unroll
;       for (int s8 = 0; s8 < 32; s8 += 8) {
; #pragma unroll
;         for (int q = 0; q < 8; q += 2) {
;           ldops(ob, s8 + q + 1);
;           step(oa, s8 + q);
;           ldops(oa, (s8 + q + 2) & 31);
;           step(ob, s8 + q + 1);
;         }
;         yw[s8 * 32] = ykeep;
;       }
	ds_read_b128 v[48:51], v117 offset:32256
	ds_read_b128 v[52:55], v117 offset:32272
	ds_read_b128 v[56:59], v117 offset:32512
	ds_read_b128 v[60:63], v117 offset:32528
	ds_read_b128 v[64:67], v117 offset:32768
	ds_read_b128 v[68:71], v117 offset:32784
	ds_read_b128 v[72:75], v117 offset:33024
	ds_read_b128 v[76:79], v117 offset:33040
	ds_read_b128 v[80:83], v117 offset:33280
	ds_read_b128 v[84:87], v117 offset:33296
	v_pk_mul_f32 v[92:93], v[0:1], v[8:9]
	v_pk_mul_f32 v[94:95], v[2:3], v[10:11]
	v_pk_fma_f32 v[92:93], v[4:5], v[12:13], v[92:93]
	v_pk_fma_f32 v[94:95], v[6:7], v[14:15], v[94:95]
	v_add_f32_dpp v114, v114, v114 quad_perm:[1,0,3,2] row_mask:0xf bank_mask:0xf bound_ctrl:1
	v_pk_add_f32 v[92:93], v[92:93], v[94:95]
	v_pk_mul_f32 v[102:103], v[32:33], v[88:89] op_sel_hi:[1,0]
	v_add_f32_dpp v114, v114, v114 quad_perm:[2,3,0,1] row_mask:0xf bank_mask:0xf bound_ctrl:1
	v_add_f32_e32 v110, v92, v93
	v_pk_mul_f32 v[104:105], v[34:35], v[88:89] op_sel_hi:[1,0]
	v_add_f32_dpp v115, v114, v114 row_half_mirror row_mask:0xf bank_mask:0xf bound_ctrl:1
	v_pk_mul_f32 v[106:107], v[36:37], v[88:89] op_sel_hi:[1,0]
	v_add_f32_dpp v110, v110, v110 quad_perm:[1,0,3,2] row_mask:0xf bank_mask:0xf bound_ctrl:1
	v_pk_mul_f32 v[108:109], v[38:39], v[88:89] op_sel_hi:[1,0]
	v_pk_fma_f32 v[0:1], v[0:1], v[16:17], v[102:103]
	v_add_f32_dpp v110, v110, v110 quad_perm:[2,3,0,1] row_mask:0xf bank_mask:0xf bound_ctrl:1
	v_pk_fma_f32 v[2:3], v[2:3], v[18:19], v[104:105]
	v_pk_fma_f32 v[4:5], v[4:5], v[20:21], v[106:107]
	v_add_f32_dpp v112, v110, v110 row_half_mirror row_mask:0xf bank_mask:0xf bound_ctrl:1
	v_pk_fma_f32 v[6:7], v[6:7], v[22:23], v[108:109]
	v_cndmask_b32_e64 v116, v116, v115, s[68:69]
	v_pk_fma_f32 v[0:1], v[24:25], v[112:113], v[0:1] op_sel_hi:[1,0,1]
	v_pk_fma_f32 v[2:3], v[26:27], v[112:113], v[2:3] op_sel_hi:[1,0,1]
	v_pk_fma_f32 v[4:5], v[28:29], v[112:113], v[4:5] op_sel_hi:[1,0,1]
	v_pk_fma_f32 v[6:7], v[30:31], v[112:113], v[6:7] op_sel_hi:[1,0,1]
	v_pk_mul_f32 v[98:99], v[0:1], v[40:41]
	v_pk_mul_f32 v[100:101], v[2:3], v[42:43]
	v_pk_fma_f32 v[98:99], v[4:5], v[44:45], v[98:99]
	v_pk_fma_f32 v[100:101], v[6:7], v[46:47], v[100:101]
	v_pk_add_f32 v[98:99], v[98:99], v[100:101]
	v_add_f32_e32 v114, v98, v99
	s_waitcnt lgkmcnt(0)
	ds_read_b128 v[8:11], v117 offset:33792
	ds_read_b128 v[12:15], v117 offset:33808
	ds_read_b128 v[16:19], v117 offset:34048
	ds_read_b128 v[20:23], v117 offset:34064
	ds_read_b128 v[24:27], v117 offset:34304
	ds_read_b128 v[28:31], v117 offset:34320
	ds_read_b128 v[32:35], v117 offset:34560
	ds_read_b128 v[36:39], v117 offset:34576
	ds_read_b128 v[40:43], v117 offset:34816
	ds_read_b128 v[44:47], v117 offset:34832
	ds_read2st64_b32 v[90:91], v118 offset0:137 offset1:143
	v_pk_mul_f32 v[92:93], v[0:1], v[48:49]
	v_pk_mul_f32 v[94:95], v[2:3], v[50:51]
	v_pk_fma_f32 v[92:93], v[4:5], v[52:53], v[92:93]
	v_pk_fma_f32 v[94:95], v[6:7], v[54:55], v[94:95]
	v_add_f32_dpp v114, v114, v114 quad_perm:[1,0,3,2] row_mask:0xf bank_mask:0xf bound_ctrl:1
	v_pk_add_f32 v[92:93], v[92:93], v[94:95]
	v_pk_mul_f32 v[102:103], v[72:73], v[88:89] op_sel:[0,1] op_sel_hi:[1,1]
	v_add_f32_dpp v114, v114, v114 quad_perm:[2,3,0,1] row_mask:0xf bank_mask:0xf bound_ctrl:1
	v_add_f32_e32 v110, v92, v93
	v_pk_mul_f32 v[104:105], v[74:75], v[88:89] op_sel:[0,1] op_sel_hi:[1,1]
	v_add_f32_dpp v115, v114, v114 row_half_mirror row_mask:0xf bank_mask:0xf bound_ctrl:1
	v_pk_mul_f32 v[106:107], v[76:77], v[88:89] op_sel:[0,1] op_sel_hi:[1,1]
	v_add_f32_dpp v110, v110, v110 quad_perm:[1,0,3,2] row_mask:0xf bank_mask:0xf bound_ctrl:1
	v_pk_mul_f32 v[108:109], v[78:79], v[88:89] op_sel:[0,1] op_sel_hi:[1,1]
	v_pk_fma_f32 v[0:1], v[0:1], v[56:57], v[102:103]
	v_add_f32_dpp v110, v110, v110 quad_perm:[2,3,0,1] row_mask:0xf bank_mask:0xf bound_ctrl:1
	v_pk_fma_f32 v[2:3], v[2:3], v[58:59], v[104:105]
	v_pk_fma_f32 v[4:5], v[4:5], v[60:61], v[106:107]
	v_add_f32_dpp v112, v110, v110 row_half_mirror row_mask:0xf bank_mask:0xf bound_ctrl:1
	v_pk_fma_f32 v[6:7], v[6:7], v[62:63], v[108:109]
	v_cndmask_b32_e64 v116, v116, v115, s[70:71]
	v_pk_fma_f32 v[0:1], v[64:65], v[112:113], v[0:1] op_sel_hi:[1,0,1]
	v_pk_fma_f32 v[2:3], v[66:67], v[112:113], v[2:3] op_sel_hi:[1,0,1]
	v_pk_fma_f32 v[4:5], v[68:69], v[112:113], v[4:5] op_sel_hi:[1,0,1]
	v_pk_fma_f32 v[6:7], v[70:71], v[112:113], v[6:7] op_sel_hi:[1,0,1]
	v_pk_mul_f32 v[98:99], v[0:1], v[80:81]
	v_pk_mul_f32 v[100:101], v[2:3], v[82:83]
	v_pk_fma_f32 v[98:99], v[4:5], v[84:85], v[98:99]
	v_pk_fma_f32 v[100:101], v[6:7], v[86:87], v[100:101]
	v_pk_add_f32 v[98:99], v[98:99], v[100:101]
	v_add_f32_e32 v114, v98, v99
	s_waitcnt lgkmcnt(0)
; DEV void scan_tile(const Params& p, int l, int tile, char* smem) {
;     ...
;       const float* cb = arr + buf * 32 * 384;
;       const int vo = 320 + half * 32 + w * 8 + r8;
;       float* yw = ybuf + buf * 1024 + cg * 32 + w * 8 + r8;
;       auto ldops = [&](ScanOps& o, int sl) {
;         const f32x4* b4 = (const f32x4*)(cb + sl * 384);
;         o.nkk0 = b4[cg * 2]; o.nkk1 = b4[cg * 2 + 1];
;         o.w0 = b4[16 + cg * 2]; o.w1 = b4[16 + cg * 2 + 1];
;         o.kka0 = b4[32 + cg * 2]; o.kka1 = b4[32 + cg * 2 + 1];
;         o.kd0 = b4[48 + cg * 2]; o.kd1 = b4[48 + cg * 2 + 1];
;         o.r0 = b4[64 + cg * 2]; o.r1 = b4[64 + cg * 2 + 1];
;         o.v = cb[sl * 384 + vo];
;       };
;       float ykeep = 0.f;
;       auto step = [&](const ScanOps& o, int sl) {
;         const f32x4 sA = S0 * o.nkk0 + S1 * o.nkk1;
;         const float sa = red8((sA[0] + sA[1]) + (sA[2] + sA[3]));
;         S0 = S0 * o.w0 + (o.kka0 * sa + o.kd0 * o.v);
;         S1 = S1 * o.w1 + (o.kka1 * sa + o.kd1 * o.v);
;         const f32x4 yA = S0 * o.r0 + S1 * o.r1;
;         const float y = red8((yA[0] + yA[1]) + (yA[2] + yA[3]));
;         ykeep = (cg == (sl & 7)) ? y : ykeep;
;       };
;       ScanOps oa, ob;
;       ldops(oa, 0);
; #pragma unroll
;       for (int s8 = 0; s8 < 32; s8 += 8) {
; #pragma unroll
;         for (int q = 0; q < 8; q += 2) {
;           ldops(ob, s8 + q + 1);
;           step(oa, s8 + q);
;           ldops(oa, (s8 + q + 2) & 31);
;           step(ob, s8 + q + 1);
;         }
;         yw[s8 * 32] = ykeep;
;       }
	ds_read_b128 v[48:51], v117 offset:35328
	ds_read_b128 v[52:55], v117 offset:35344
	ds_read_b128 v[56:59], v117 offset:35584
	ds_read_b128 v[60:63], v117 offset:35600
	ds_read_b128 v[64:67], v117 offset:35840
	ds_read_b128 v[68:71], v117 offset:35856
	ds_read_b128 v[72:75], v117 offset:36096
	ds_read_b128 v[76:79], v117 offset:36112
	ds_read_b128 v[80:83], v117 offset:36352
	ds_read_b128 v[84:87], v117 offset:36368
	v_pk_mul_f32 v[92:93], v[0:1], v[8:9]
	v_pk_mul_f32 v[94:95], v[2:3], v[10:11]
	v_pk_fma_f32 v[92:93], v[4:5], v[12:13], v[92:93]
	v_pk_fma_f32 v[94:95], v[6:7], v[14:15], v[94:95]
	v_add_f32_dpp v114, v114, v114 quad_perm:[1,0,3,2] row_mask:0xf bank_mask:0xf bound_ctrl:1
	v_pk_add_f32 v[92:93], v[92:93], v[94:95]
	v_pk_mul_f32 v[102:103], v[32:33], v[90:91] op_sel_hi:[1,0]
	v_add_f32_dpp v114, v114, v114 quad_perm:[2,3,0,1] row_mask:0xf bank_mask:0xf bound_ctrl:1
	v_add_f32_e32 v110, v92, v93
	v_pk_mul_f32 v[104:105], v[34:35], v[90:91] op_sel_hi:[1,0]
	v_add_f32_dpp v115, v114, v114 row_half_mirror row_mask:0xf bank_mask:0xf bound_ctrl:1
	v_pk_mul_f32 v[106:107], v[36:37], v[90:91] op_sel_hi:[1,0]
	v_add_f32_dpp v110, v110, v110 quad_perm:[1,0,3,2] row_mask:0xf bank_mask:0xf bound_ctrl:1
	v_pk_mul_f32 v[108:109], v[38:39], v[90:91] op_sel_hi:[1,0]
	v_pk_fma_f32 v[0:1], v[0:1], v[16:17], v[102:103]
	v_add_f32_dpp v110, v110, v110 quad_perm:[2,3,0,1] row_mask:0xf bank_mask:0xf bound_ctrl:1
	v_pk_fma_f32 v[2:3], v[2:3], v[18:19], v[104:105]
	v_pk_fma_f32 v[4:5], v[4:5], v[20:21], v[106:107]
	v_add_f32_dpp v112, v110, v110 row_half_mirror row_mask:0xf bank_mask:0xf bound_ctrl:1
	v_pk_fma_f32 v[6:7], v[6:7], v[22:23], v[108:109]
	v_cndmask_b32_e64 v116, v116, v115, s[0:1]
	v_pk_fma_f32 v[0:1], v[24:25], v[112:113], v[0:1] op_sel_hi:[1,0,1]
	v_pk_fma_f32 v[2:3], v[26:27], v[112:113], v[2:3] op_sel_hi:[1,0,1]
	v_pk_fma_f32 v[4:5], v[28:29], v[112:113], v[4:5] op_sel_hi:[1,0,1]
	v_pk_fma_f32 v[6:7], v[30:31], v[112:113], v[6:7] op_sel_hi:[1,0,1]
	v_pk_mul_f32 v[98:99], v[0:1], v[40:41]
	v_pk_mul_f32 v[100:101], v[2:3], v[42:43]
	v_pk_fma_f32 v[98:99], v[4:5], v[44:45], v[98:99]
	v_pk_fma_f32 v[100:101], v[6:7], v[46:47], v[100:101]
	v_pk_add_f32 v[98:99], v[98:99], v[100:101]
	v_add_f32_e32 v114, v98, v99
	s_waitcnt lgkmcnt(0)
	ds_read_b128 v[8:11], v117 offset:36864
	ds_read_b128 v[12:15], v117 offset:36880
	ds_read_b128 v[16:19], v117 offset:37120
	ds_read_b128 v[20:23], v117 offset:37136
	ds_read_b128 v[24:27], v117 offset:37376
	ds_read_b128 v[28:31], v117 offset:37392
	ds_read_b128 v[32:35], v117 offset:37632
	ds_read_b128 v[36:39], v117 offset:37648
	ds_read_b128 v[40:43], v117 offset:37888
	ds_read_b128 v[44:47], v117 offset:37904
	ds_read2st64_b32 v[88:89], v118 offset0:149 offset1:155
	v_pk_mul_f32 v[92:93], v[0:1], v[48:49]
	v_pk_mul_f32 v[94:95], v[2:3], v[50:51]
	v_pk_fma_f32 v[92:93], v[4:5], v[52:53], v[92:93]
	v_pk_fma_f32 v[94:95], v[6:7], v[54:55], v[94:95]
	v_add_f32_dpp v114, v114, v114 quad_perm:[1,0,3,2] row_mask:0xf bank_mask:0xf bound_ctrl:1
	v_pk_add_f32 v[92:93], v[92:93], v[94:95]
	v_pk_mul_f32 v[102:103], v[72:73], v[90:91] op_sel:[0,1] op_sel_hi:[1,1]
	v_add_f32_dpp v114, v114, v114 quad_perm:[2,3,0,1] row_mask:0xf bank_mask:0xf bound_ctrl:1
	v_add_f32_e32 v110, v92, v93
	v_pk_mul_f32 v[104:105], v[74:75], v[90:91] op_sel:[0,1] op_sel_hi:[1,1]
	v_add_f32_dpp v115, v114, v114 row_half_mirror row_mask:0xf bank_mask:0xf bound_ctrl:1
	v_pk_mul_f32 v[106:107], v[76:77], v[90:91] op_sel:[0,1] op_sel_hi:[1,1]
	v_add_f32_dpp v110, v110, v110 quad_perm:[1,0,3,2] row_mask:0xf bank_mask:0xf bound_ctrl:1
	v_pk_mul_f32 v[108:109], v[78:79], v[90:91] op_sel:[0,1] op_sel_hi:[1,1]
	v_pk_fma_f32 v[0:1], v[0:1], v[56:57], v[102:103]
	v_add_f32_dpp v110, v110, v110 quad_perm:[2,3,0,1] row_mask:0xf bank_mask:0xf bound_ctrl:1
	v_pk_fma_f32 v[2:3], v[2:3], v[58:59], v[104:105]
	v_pk_fma_f32 v[4:5], v[4:5], v[60:61], v[106:107]
	v_add_f32_dpp v112, v110, v110 row_half_mirror row_mask:0xf bank_mask:0xf bound_ctrl:1
	v_pk_fma_f32 v[6:7], v[6:7], v[62:63], v[108:109]
	v_cndmask_b32_e64 v116, v116, v115, s[96:97]
	v_pk_fma_f32 v[0:1], v[64:65], v[112:113], v[0:1] op_sel_hi:[1,0,1]
	v_pk_fma_f32 v[2:3], v[66:67], v[112:113], v[2:3] op_sel_hi:[1,0,1]
	v_pk_fma_f32 v[4:5], v[68:69], v[112:113], v[4:5] op_sel_hi:[1,0,1]
	v_pk_fma_f32 v[6:7], v[70:71], v[112:113], v[6:7] op_sel_hi:[1,0,1]
	v_pk_mul_f32 v[98:99], v[0:1], v[80:81]
	v_pk_mul_f32 v[100:101], v[2:3], v[82:83]
	v_pk_fma_f32 v[98:99], v[4:5], v[84:85], v[98:99]
	v_pk_fma_f32 v[100:101], v[6:7], v[86:87], v[100:101]
	v_pk_add_f32 v[98:99], v[98:99], v[100:101]
	v_add_f32_e32 v114, v98, v99
	s_waitcnt lgkmcnt(0)
; DEV void scan_tile(const Params& p, int l, int tile, char* smem) {
;     ...
;       const float* cb = arr + buf * 32 * 384;
;       const int vo = 320 + half * 32 + w * 8 + r8;
;       float* yw = ybuf + buf * 1024 + cg * 32 + w * 8 + r8;
;       auto ldops = [&](ScanOps& o, int sl) {
;         const f32x4* b4 = (const f32x4*)(cb + sl * 384);
;         o.nkk0 = b4[cg * 2]; o.nkk1 = b4[cg * 2 + 1];
;         o.w0 = b4[16 + cg * 2]; o.w1 = b4[16 + cg * 2 + 1];
;         o.kka0 = b4[32 + cg * 2]; o.kka1 = b4[32 + cg * 2 + 1];
;         o.kd0 = b4[48 + cg * 2]; o.kd1 = b4[48 + cg * 2 + 1];
;         o.r0 = b4[64 + cg * 2]; o.r1 = b4[64 + cg * 2 + 1];
;         o.v = cb[sl * 384 + vo];
;       };
;       float ykeep = 0.f;
;       auto step = [&](const ScanOps& o, int sl) {
;         const f32x4 sA = S0 * o.nkk0 + S1 * o.nkk1;
;         const float sa = red8((sA[0] + sA[1]) + (sA[2] + sA[3]));
;         S0 = S0 * o.w0 + (o.kka0 * sa + o.kd0 * o.v);
;         S1 = S1 * o.w1 + (o.kka1 * sa + o.kd1 * o.v);
;         const f32x4 yA = S0 * o.r0 + S1 * o.r1;
;         const float y = red8((yA[0] + yA[1]) + (yA[2] + yA[3]));
;         ykeep = (cg == (sl & 7)) ? y : ykeep;
;       };
;       ScanOps oa, ob;
;       ldops(oa, 0);
; #pragma unroll
;       for (int s8 = 0; s8 < 32; s8 += 8) {
; #pragma unroll
;         for (int q = 0; q < 8; q += 2) {
;           ldops(ob, s8 + q + 1);
;           step(oa, s8 + q);
;           ldops(oa, (s8 + q + 2) & 31);
;           step(ob, s8 + q + 1);
;         }
;         yw[s8 * 32] = ykeep;
;       }
	ds_read_b128 v[48:51], v117 offset:38400
	ds_read_b128 v[52:55], v117 offset:38416
	ds_read_b128 v[56:59], v117 offset:38656
	ds_read_b128 v[60:63], v117 offset:38672
	ds_read_b128 v[64:67], v117 offset:38912
	ds_read_b128 v[68:71], v117 offset:38928
	ds_read_b128 v[72:75], v117 offset:39168
	ds_read_b128 v[76:79], v117 offset:39184
	ds_read_b128 v[80:83], v117 offset:39424
	ds_read_b128 v[84:87], v117 offset:39440
	v_pk_mul_f32 v[92:93], v[0:1], v[8:9]
	v_pk_mul_f32 v[94:95], v[2:3], v[10:11]
	v_pk_fma_f32 v[92:93], v[4:5], v[12:13], v[92:93]
	v_pk_fma_f32 v[94:95], v[6:7], v[14:15], v[94:95]
	v_add_f32_dpp v114, v114, v114 quad_perm:[1,0,3,2] row_mask:0xf bank_mask:0xf bound_ctrl:1
	v_pk_add_f32 v[92:93], v[92:93], v[94:95]
	v_pk_mul_f32 v[102:103], v[32:33], v[88:89] op_sel_hi:[1,0]
	v_add_f32_dpp v114, v114, v114 quad_perm:[2,3,0,1] row_mask:0xf bank_mask:0xf bound_ctrl:1
	v_add_f32_e32 v110, v92, v93
	v_pk_mul_f32 v[104:105], v[34:35], v[88:89] op_sel_hi:[1,0]
	v_add_f32_dpp v115, v114, v114 row_half_mirror row_mask:0xf bank_mask:0xf bound_ctrl:1
	v_pk_mul_f32 v[106:107], v[36:37], v[88:89] op_sel_hi:[1,0]
	v_add_f32_dpp v110, v110, v110 quad_perm:[1,0,3,2] row_mask:0xf bank_mask:0xf bound_ctrl:1
	v_pk_mul_f32 v[108:109], v[38:39], v[88:89] op_sel_hi:[1,0]
	v_pk_fma_f32 v[0:1], v[0:1], v[16:17], v[102:103]
	v_add_f32_dpp v110, v110, v110 quad_perm:[2,3,0,1] row_mask:0xf bank_mask:0xf bound_ctrl:1
	v_pk_fma_f32 v[2:3], v[2:3], v[18:19], v[104:105]
	v_pk_fma_f32 v[4:5], v[4:5], v[20:21], v[106:107]
	v_add_f32_dpp v112, v110, v110 row_half_mirror row_mask:0xf bank_mask:0xf bound_ctrl:1
	v_pk_fma_f32 v[6:7], v[6:7], v[22:23], v[108:109]
	v_cndmask_b32_e64 v116, v116, v115, vcc
	ds_write_b32 v119, v116 offset:2048
	v_pk_fma_f32 v[0:1], v[24:25], v[112:113], v[0:1] op_sel_hi:[1,0,1]
	v_pk_fma_f32 v[2:3], v[26:27], v[112:113], v[2:3] op_sel_hi:[1,0,1]
	v_pk_fma_f32 v[4:5], v[28:29], v[112:113], v[4:5] op_sel_hi:[1,0,1]
	v_pk_fma_f32 v[6:7], v[30:31], v[112:113], v[6:7] op_sel_hi:[1,0,1]
	v_pk_mul_f32 v[98:99], v[0:1], v[40:41]
	v_pk_mul_f32 v[100:101], v[2:3], v[42:43]
	v_pk_fma_f32 v[98:99], v[4:5], v[44:45], v[98:99]
	v_pk_fma_f32 v[100:101], v[6:7], v[46:47], v[100:101]
	v_pk_add_f32 v[98:99], v[98:99], v[100:101]
	v_add_f32_e32 v114, v98, v99
	s_waitcnt lgkmcnt(1)
	ds_read_b128 v[8:11], v117 offset:39936
	ds_read_b128 v[12:15], v117 offset:39952
	ds_read_b128 v[16:19], v117 offset:40192
	ds_read_b128 v[20:23], v117 offset:40208
	ds_read_b128 v[24:27], v117 offset:40448
	ds_read_b128 v[28:31], v117 offset:40464
	ds_read_b128 v[32:35], v117 offset:40704
	ds_read_b128 v[36:39], v117 offset:40720
	ds_read_b128 v[40:43], v117 offset:40960
	ds_read_b128 v[44:47], v117 offset:40976
	ds_read2st64_b32 v[90:91], v118 offset0:161 offset1:167
	v_pk_mul_f32 v[92:93], v[0:1], v[48:49]
	v_pk_mul_f32 v[94:95], v[2:3], v[50:51]
	v_pk_fma_f32 v[92:93], v[4:5], v[52:53], v[92:93]
	v_pk_fma_f32 v[94:95], v[6:7], v[54:55], v[94:95]
	v_add_f32_dpp v114, v114, v114 quad_perm:[1,0,3,2] row_mask:0xf bank_mask:0xf bound_ctrl:1
	v_pk_add_f32 v[92:93], v[92:93], v[94:95]
	v_pk_mul_f32 v[102:103], v[72:73], v[88:89] op_sel:[0,1] op_sel_hi:[1,1]
	v_add_f32_dpp v114, v114, v114 quad_perm:[2,3,0,1] row_mask:0xf bank_mask:0xf bound_ctrl:1
	v_add_f32_e32 v110, v92, v93
	v_pk_mul_f32 v[104:105], v[74:75], v[88:89] op_sel:[0,1] op_sel_hi:[1,1]
	v_add_f32_dpp v115, v114, v114 row_half_mirror row_mask:0xf bank_mask:0xf bound_ctrl:1
	v_pk_mul_f32 v[106:107], v[76:77], v[88:89] op_sel:[0,1] op_sel_hi:[1,1]
	v_add_f32_dpp v110, v110, v110 quad_perm:[1,0,3,2] row_mask:0xf bank_mask:0xf bound_ctrl:1
	v_pk_mul_f32 v[108:109], v[78:79], v[88:89] op_sel:[0,1] op_sel_hi:[1,1]
	v_pk_fma_f32 v[0:1], v[0:1], v[56:57], v[102:103]
	v_add_f32_dpp v110, v110, v110 quad_perm:[2,3,0,1] row_mask:0xf bank_mask:0xf bound_ctrl:1
	v_pk_fma_f32 v[2:3], v[2:3], v[58:59], v[104:105]
	v_pk_fma_f32 v[4:5], v[4:5], v[60:61], v[106:107]
	v_add_f32_dpp v112, v110, v110 row_half_mirror row_mask:0xf bank_mask:0xf bound_ctrl:1
	v_pk_fma_f32 v[6:7], v[6:7], v[62:63], v[108:109]
	v_cndmask_b32_e64 v116, v116, v115, s[62:63]
	v_pk_fma_f32 v[0:1], v[64:65], v[112:113], v[0:1] op_sel_hi:[1,0,1]
	v_pk_fma_f32 v[2:3], v[66:67], v[112:113], v[2:3] op_sel_hi:[1,0,1]
	v_pk_fma_f32 v[4:5], v[68:69], v[112:113], v[4:5] op_sel_hi:[1,0,1]
	v_pk_fma_f32 v[6:7], v[70:71], v[112:113], v[6:7] op_sel_hi:[1,0,1]
	v_pk_mul_f32 v[98:99], v[0:1], v[80:81]
	v_pk_mul_f32 v[100:101], v[2:3], v[82:83]
	v_pk_fma_f32 v[98:99], v[4:5], v[84:85], v[98:99]
	v_pk_fma_f32 v[100:101], v[6:7], v[86:87], v[100:101]
	v_pk_add_f32 v[98:99], v[98:99], v[100:101]
	v_add_f32_e32 v114, v98, v99
	s_waitcnt lgkmcnt(0)
; DEV void scan_tile(const Params& p, int l, int tile, char* smem) {
;     ...
;       const float* cb = arr + buf * 32 * 384;
;       const int vo = 320 + half * 32 + w * 8 + r8;
;       float* yw = ybuf + buf * 1024 + cg * 32 + w * 8 + r8;
;       auto ldops = [&](ScanOps& o, int sl) {
;         const f32x4* b4 = (const f32x4*)(cb + sl * 384);
;         o.nkk0 = b4[cg * 2]; o.nkk1 = b4[cg * 2 + 1];
;         o.w0 = b4[16 + cg * 2]; o.w1 = b4[16 + cg * 2 + 1];
;         o.kka0 = b4[32 + cg * 2]; o.kka1 = b4[32 + cg * 2 + 1];
;         o.kd0 = b4[48 + cg * 2]; o.kd1 = b4[48 + cg * 2 + 1];
;         o.r0 = b4[64 + cg * 2]; o.r1 = b4[64 + cg * 2 + 1];
;         o.v = cb[sl * 384 + vo];
;       };
;       float ykeep = 0.f;
;       auto step = [&](const ScanOps& o, int sl) {
;         const f32x4 sA = S0 * o.nkk0 + S1 * o.nkk1;
;         const float sa = red8((sA[0] + sA[1]) + (sA[2] + sA[3]));
;         S0 = S0 * o.w0 + (o.kka0 * sa + o.kd0 * o.v);
;         S1 = S1 * o.w1 + (o.kka1 * sa + o.kd1 * o.v);
;         const f32x4 yA = S0 * o.r0 + S1 * o.r1;
;         const float y = red8((yA[0] + yA[1]) + (yA[2] + yA[3]));
;         ykeep = (cg == (sl & 7)) ? y : ykeep;
;       };
;       ScanOps oa, ob;
;       ldops(oa, 0);
; #pragma unroll
;       for (int s8 = 0; s8 < 32; s8 += 8) {
; #pragma unroll
;         for (int q = 0; q < 8; q += 2) {
;           ldops(ob, s8 + q + 1);
;           step(oa, s8 + q);
;           ldops(oa, (s8 + q + 2) & 31);
;           step(ob, s8 + q + 1);
;         }
;         yw[s8 * 32] = ykeep;
;       }
	ds_read_b128 v[48:51], v117 offset:41472
	ds_read_b128 v[52:55], v117 offset:41488
	ds_read_b128 v[56:59], v117 offset:41728
	ds_read_b128 v[60:63], v117 offset:41744
	ds_read_b128 v[64:67], v117 offset:41984
	ds_read_b128 v[68:71], v117 offset:42000
	ds_read_b128 v[72:75], v117 offset:42240
	ds_read_b128 v[76:79], v117 offset:42256
	ds_read_b128 v[80:83], v117 offset:42496
	ds_read_b128 v[84:87], v117 offset:42512
	v_pk_mul_f32 v[92:93], v[0:1], v[8:9]
	v_pk_mul_f32 v[94:95], v[2:3], v[10:11]
	v_pk_fma_f32 v[92:93], v[4:5], v[12:13], v[92:93]
	v_pk_fma_f32 v[94:95], v[6:7], v[14:15], v[94:95]
	v_add_f32_dpp v114, v114, v114 quad_perm:[1,0,3,2] row_mask:0xf bank_mask:0xf bound_ctrl:1
	v_pk_add_f32 v[92:93], v[92:93], v[94:95]
	v_pk_mul_f32 v[102:103], v[32:33], v[90:91] op_sel_hi:[1,0]
	v_add_f32_dpp v114, v114, v114 quad_perm:[2,3,0,1] row_mask:0xf bank_mask:0xf bound_ctrl:1
	v_add_f32_e32 v110, v92, v93
	v_pk_mul_f32 v[104:105], v[34:35], v[90:91] op_sel_hi:[1,0]
	v_add_f32_dpp v115, v114, v114 row_half_mirror row_mask:0xf bank_mask:0xf bound_ctrl:1
	v_pk_mul_f32 v[106:107], v[36:37], v[90:91] op_sel_hi:[1,0]
	v_add_f32_dpp v110, v110, v110 quad_perm:[1,0,3,2] row_mask:0xf bank_mask:0xf bound_ctrl:1
	v_pk_mul_f32 v[108:109], v[38:39], v[90:91] op_sel_hi:[1,0]
	v_pk_fma_f32 v[0:1], v[0:1], v[16:17], v[102:103]
	v_add_f32_dpp v110, v110, v110 quad_perm:[2,3,0,1] row_mask:0xf bank_mask:0xf bound_ctrl:1
	v_pk_fma_f32 v[2:3], v[2:3], v[18:19], v[104:105]
	v_pk_fma_f32 v[4:5], v[4:5], v[20:21], v[106:107]
	v_add_f32_dpp v112, v110, v110 row_half_mirror row_mask:0xf bank_mask:0xf bound_ctrl:1
	v_pk_fma_f32 v[6:7], v[6:7], v[22:23], v[108:109]
	v_cndmask_b32_e64 v116, v116, v115, s[64:65]
	v_pk_fma_f32 v[0:1], v[24:25], v[112:113], v[0:1] op_sel_hi:[1,0,1]
	v_pk_fma_f32 v[2:3], v[26:27], v[112:113], v[2:3] op_sel_hi:[1,0,1]
	v_pk_fma_f32 v[4:5], v[28:29], v[112:113], v[4:5] op_sel_hi:[1,0,1]
	v_pk_fma_f32 v[6:7], v[30:31], v[112:113], v[6:7] op_sel_hi:[1,0,1]
	v_pk_mul_f32 v[98:99], v[0:1], v[40:41]
	v_pk_mul_f32 v[100:101], v[2:3], v[42:43]
	v_pk_fma_f32 v[98:99], v[4:5], v[44:45], v[98:99]
	v_pk_fma_f32 v[100:101], v[6:7], v[46:47], v[100:101]
	v_pk_add_f32 v[98:99], v[98:99], v[100:101]
	v_add_f32_e32 v114, v98, v99
	s_waitcnt lgkmcnt(0)
	ds_read_b128 v[8:11], v117 offset:43008
	ds_read_b128 v[12:15], v117 offset:43024
	ds_read_b128 v[16:19], v117 offset:43264
	ds_read_b128 v[20:23], v117 offset:43280
	ds_read_b128 v[24:27], v117 offset:43520
	ds_read_b128 v[28:31], v117 offset:43536
	ds_read_b128 v[32:35], v117 offset:43776
	ds_read_b128 v[36:39], v117 offset:43792
	ds_read_b128 v[40:43], v117 offset:44032
	ds_read_b128 v[44:47], v117 offset:44048
	ds_read2st64_b32 v[88:89], v118 offset0:173 offset1:179
	v_pk_mul_f32 v[92:93], v[0:1], v[48:49]
	v_pk_mul_f32 v[94:95], v[2:3], v[50:51]
	v_pk_fma_f32 v[92:93], v[4:5], v[52:53], v[92:93]
	v_pk_fma_f32 v[94:95], v[6:7], v[54:55], v[94:95]
	v_add_f32_dpp v114, v114, v114 quad_perm:[1,0,3,2] row_mask:0xf bank_mask:0xf bound_ctrl:1
	v_pk_add_f32 v[92:93], v[92:93], v[94:95]
	v_pk_mul_f32 v[102:103], v[72:73], v[90:91] op_sel:[0,1] op_sel_hi:[1,1]
	v_add_f32_dpp v114, v114, v114 quad_perm:[2,3,0,1] row_mask:0xf bank_mask:0xf bound_ctrl:1
	v_add_f32_e32 v110, v92, v93
	v_pk_mul_f32 v[104:105], v[74:75], v[90:91] op_sel:[0,1] op_sel_hi:[1,1]
	v_add_f32_dpp v115, v114, v114 row_half_mirror row_mask:0xf bank_mask:0xf bound_ctrl:1
	v_pk_mul_f32 v[106:107], v[76:77], v[90:91] op_sel:[0,1] op_sel_hi:[1,1]
	v_add_f32_dpp v110, v110, v110 quad_perm:[1,0,3,2] row_mask:0xf bank_mask:0xf bound_ctrl:1
	v_pk_mul_f32 v[108:109], v[78:79], v[90:91] op_sel:[0,1] op_sel_hi:[1,1]
	v_pk_fma_f32 v[0:1], v[0:1], v[56:57], v[102:103]
	v_add_f32_dpp v110, v110, v110 quad_perm:[2,3,0,1] row_mask:0xf bank_mask:0xf bound_ctrl:1
	v_pk_fma_f32 v[2:3], v[2:3], v[58:59], v[104:105]
	v_pk_fma_f32 v[4:5], v[4:5], v[60:61], v[106:107]
	v_add_f32_dpp v112, v110, v110 row_half_mirror row_mask:0xf bank_mask:0xf bound_ctrl:1
	v_pk_fma_f32 v[6:7], v[6:7], v[62:63], v[108:109]
	v_cndmask_b32_e64 v116, v116, v115, s[66:67]
	v_pk_fma_f32 v[0:1], v[64:65], v[112:113], v[0:1] op_sel_hi:[1,0,1]
	v_pk_fma_f32 v[2:3], v[66:67], v[112:113], v[2:3] op_sel_hi:[1,0,1]
	v_pk_fma_f32 v[4:5], v[68:69], v[112:113], v[4:5] op_sel_hi:[1,0,1]
	v_pk_fma_f32 v[6:7], v[70:71], v[112:113], v[6:7] op_sel_hi:[1,0,1]
	v_pk_mul_f32 v[98:99], v[0:1], v[80:81]
	v_pk_mul_f32 v[100:101], v[2:3], v[82:83]
	v_pk_fma_f32 v[98:99], v[4:5], v[84:85], v[98:99]
	v_pk_fma_f32 v[100:101], v[6:7], v[86:87], v[100:101]
	v_pk_add_f32 v[98:99], v[98:99], v[100:101]
	v_add_f32_e32 v114, v98, v99
	s_waitcnt lgkmcnt(0)
; DEV void scan_tile(const Params& p, int l, int tile, char* smem) {
;     ...
;       const float* cb = arr + buf * 32 * 384;
;       const int vo = 320 + half * 32 + w * 8 + r8;
;       float* yw = ybuf + buf * 1024 + cg * 32 + w * 8 + r8;
;       auto ldops = [&](ScanOps& o, int sl) {
;         const f32x4* b4 = (const f32x4*)(cb + sl * 384);
;         o.nkk0 = b4[cg * 2]; o.nkk1 = b4[cg * 2 + 1];
;         o.w0 = b4[16 + cg * 2]; o.w1 = b4[16 + cg * 2 + 1];
;         o.kka0 = b4[32 + cg * 2]; o.kka1 = b4[32 + cg * 2 + 1];
;         o.kd0 = b4[48 + cg * 2]; o.kd1 = b4[48 + cg * 2 + 1];
;         o.r0 = b4[64 + cg * 2]; o.r1 = b4[64 + cg * 2 + 1];
;         o.v = cb[sl * 384 + vo];
;       };
;       float ykeep = 0.f;
;       auto step = [&](const ScanOps& o, int sl) {
;         const f32x4 sA = S0 * o.nkk0 + S1 * o.nkk1;
;         const float sa = red8((sA[0] + sA[1]) + (sA[2] + sA[3]));
;         S0 = S0 * o.w0 + (o.kka0 * sa + o.kd0 * o.v);
;         S1 = S1 * o.w1 + (o.kka1 * sa + o.kd1 * o.v);
;         const f32x4 yA = S0 * o.r0 + S1 * o.r1;
;         const float y = red8((yA[0] + yA[1]) + (yA[2] + yA[3]));
;         ykeep = (cg == (sl & 7)) ? y : ykeep;
;       };
;       ScanOps oa, ob;
;       ldops(oa, 0);
; #pragma unroll
;       for (int s8 = 0; s8 < 32; s8 += 8) {
; #pragma unroll
;         for (int q = 0; q < 8; q += 2) {
;           ldops(ob, s8 + q + 1);
;           step(oa, s8 + q);
;           ldops(oa, (s8 + q + 2) & 31);
;           step(ob, s8 + q + 1);
;         }
;         yw[s8 * 32] = ykeep;
;       }
	ds_read_b128 v[48:51], v117 offset:44544
	ds_read_b128 v[52:55], v117 offset:44560
	ds_read_b128 v[56:59], v117 offset:44800
	ds_read_b128 v[60:63], v117 offset:44816
	ds_read_b128 v[64:67], v117 offset:45056
	ds_read_b128 v[68:71], v117 offset:45072
	ds_read_b128 v[72:75], v117 offset:45312
	ds_read_b128 v[76:79], v117 offset:45328
	ds_read_b128 v[80:83], v117 offset:45568
	ds_read_b128 v[84:87], v117 offset:45584
	v_pk_mul_f32 v[92:93], v[0:1], v[8:9]
	v_pk_mul_f32 v[94:95], v[2:3], v[10:11]
	v_pk_fma_f32 v[92:93], v[4:5], v[12:13], v[92:93]
	v_pk_fma_f32 v[94:95], v[6:7], v[14:15], v[94:95]
	v_add_f32_dpp v114, v114, v114 quad_perm:[1,0,3,2] row_mask:0xf bank_mask:0xf bound_ctrl:1
	v_pk_add_f32 v[92:93], v[92:93], v[94:95]
	v_pk_mul_f32 v[102:103], v[32:33], v[88:89] op_sel_hi:[1,0]
	v_add_f32_dpp v114, v114, v114 quad_perm:[2,3,0,1] row_mask:0xf bank_mask:0xf bound_ctrl:1
	v_add_f32_e32 v110, v92, v93
	v_pk_mul_f32 v[104:105], v[34:35], v[88:89] op_sel_hi:[1,0]
	v_add_f32_dpp v115, v114, v114 row_half_mirror row_mask:0xf bank_mask:0xf bound_ctrl:1
	v_pk_mul_f32 v[106:107], v[36:37], v[88:89] op_sel_hi:[1,0]
	v_add_f32_dpp v110, v110, v110 quad_perm:[1,0,3,2] row_mask:0xf bank_mask:0xf bound_ctrl:1
	v_pk_mul_f32 v[108:109], v[38:39], v[88:89] op_sel_hi:[1,0]
	v_pk_fma_f32 v[0:1], v[0:1], v[16:17], v[102:103]
	v_add_f32_dpp v110, v110, v110 quad_perm:[2,3,0,1] row_mask:0xf bank_mask:0xf bound_ctrl:1
	v_pk_fma_f32 v[2:3], v[2:3], v[18:19], v[104:105]
	v_pk_fma_f32 v[4:5], v[4:5], v[20:21], v[106:107]
	v_add_f32_dpp v112, v110, v110 row_half_mirror row_mask:0xf bank_mask:0xf bound_ctrl:1
	v_pk_fma_f32 v[6:7], v[6:7], v[22:23], v[108:109]
	v_cndmask_b32_e64 v116, v116, v115, s[68:69]
	v_pk_fma_f32 v[0:1], v[24:25], v[112:113], v[0:1] op_sel_hi:[1,0,1]
	v_pk_fma_f32 v[2:3], v[26:27], v[112:113], v[2:3] op_sel_hi:[1,0,1]
	v_pk_fma_f32 v[4:5], v[28:29], v[112:113], v[4:5] op_sel_hi:[1,0,1]
	v_pk_fma_f32 v[6:7], v[30:31], v[112:113], v[6:7] op_sel_hi:[1,0,1]
	v_pk_mul_f32 v[98:99], v[0:1], v[40:41]
	v_pk_mul_f32 v[100:101], v[2:3], v[42:43]
	v_pk_fma_f32 v[98:99], v[4:5], v[44:45], v[98:99]
	v_pk_fma_f32 v[100:101], v[6:7], v[46:47], v[100:101]
	v_pk_add_f32 v[98:99], v[98:99], v[100:101]
	v_add_f32_e32 v114, v98, v99
	s_waitcnt lgkmcnt(0)
	ds_read_b128 v[8:11], v117 offset:46080
	ds_read_b128 v[12:15], v117 offset:46096
	ds_read_b128 v[16:19], v117 offset:46336
	ds_read_b128 v[20:23], v117 offset:46352
	ds_read_b128 v[24:27], v117 offset:46592
	ds_read_b128 v[28:31], v117 offset:46608
	ds_read_b128 v[32:35], v117 offset:46848
	ds_read_b128 v[36:39], v117 offset:46864
	ds_read_b128 v[40:43], v117 offset:47104
	ds_read_b128 v[44:47], v117 offset:47120
	ds_read2st64_b32 v[90:91], v118 offset0:185 offset1:191
	v_pk_mul_f32 v[92:93], v[0:1], v[48:49]
	v_pk_mul_f32 v[94:95], v[2:3], v[50:51]
	v_pk_fma_f32 v[92:93], v[4:5], v[52:53], v[92:93]
	v_pk_fma_f32 v[94:95], v[6:7], v[54:55], v[94:95]
	v_add_f32_dpp v114, v114, v114 quad_perm:[1,0,3,2] row_mask:0xf bank_mask:0xf bound_ctrl:1
	v_pk_add_f32 v[92:93], v[92:93], v[94:95]
	v_pk_mul_f32 v[102:103], v[72:73], v[88:89] op_sel:[0,1] op_sel_hi:[1,1]
	v_add_f32_dpp v114, v114, v114 quad_perm:[2,3,0,1] row_mask:0xf bank_mask:0xf bound_ctrl:1
	v_add_f32_e32 v110, v92, v93
	v_pk_mul_f32 v[104:105], v[74:75], v[88:89] op_sel:[0,1] op_sel_hi:[1,1]
	v_add_f32_dpp v115, v114, v114 row_half_mirror row_mask:0xf bank_mask:0xf bound_ctrl:1
	v_pk_mul_f32 v[106:107], v[76:77], v[88:89] op_sel:[0,1] op_sel_hi:[1,1]
	v_add_f32_dpp v110, v110, v110 quad_perm:[1,0,3,2] row_mask:0xf bank_mask:0xf bound_ctrl:1
	v_pk_mul_f32 v[108:109], v[78:79], v[88:89] op_sel:[0,1] op_sel_hi:[1,1]
	v_pk_fma_f32 v[0:1], v[0:1], v[56:57], v[102:103]
	v_add_f32_dpp v110, v110, v110 quad_perm:[2,3,0,1] row_mask:0xf bank_mask:0xf bound_ctrl:1
	v_pk_fma_f32 v[2:3], v[2:3], v[58:59], v[104:105]
	v_pk_fma_f32 v[4:5], v[4:5], v[60:61], v[106:107]
	v_add_f32_dpp v112, v110, v110 row_half_mirror row_mask:0xf bank_mask:0xf bound_ctrl:1
	v_pk_fma_f32 v[6:7], v[6:7], v[62:63], v[108:109]
	v_cndmask_b32_e64 v116, v116, v115, s[70:71]
	v_pk_fma_f32 v[0:1], v[64:65], v[112:113], v[0:1] op_sel_hi:[1,0,1]
	v_pk_fma_f32 v[2:3], v[66:67], v[112:113], v[2:3] op_sel_hi:[1,0,1]
	v_pk_fma_f32 v[4:5], v[68:69], v[112:113], v[4:5] op_sel_hi:[1,0,1]
	v_pk_fma_f32 v[6:7], v[70:71], v[112:113], v[6:7] op_sel_hi:[1,0,1]
	v_pk_mul_f32 v[98:99], v[0:1], v[80:81]
	v_pk_mul_f32 v[100:101], v[2:3], v[82:83]
	v_pk_fma_f32 v[98:99], v[4:5], v[84:85], v[98:99]
	v_pk_fma_f32 v[100:101], v[6:7], v[86:87], v[100:101]
	v_pk_add_f32 v[98:99], v[98:99], v[100:101]
	v_add_f32_e32 v114, v98, v99
	s_waitcnt lgkmcnt(0)
; DEV void scan_tile(const Params& p, int l, int tile, char* smem) {
;     ...
;       auto step = [&](const ScanOps& o, int sl) {
;         const f32x4 sA = S0 * o.nkk0 + S1 * o.nkk1;
;         const float sa = red8((sA[0] + sA[1]) + (sA[2] + sA[3]));
;         S0 = S0 * o.w0 + (o.kka0 * sa + o.kd0 * o.v);
;         S1 = S1 * o.w1 + (o.kka1 * sa + o.kd1 * o.v);
;         const f32x4 yA = S0 * o.r0 + S1 * o.r1;
;         const float y = red8((yA[0] + yA[1]) + (yA[2] + yA[3]));
;         ykeep = (cg == (sl & 7)) ? y : ykeep;
;       };
;       ScanOps oa, ob;
;       ldops(oa, 0);
; #pragma unroll
;       for (int s8 = 0; s8 < 32; s8 += 8) {
; #pragma unroll
;         for (int q = 0; q < 8; q += 2) {
;           ldops(ob, s8 + q + 1);
;           step(oa, s8 + q);
;           ldops(oa, (s8 + q + 2) & 31);
;           step(ob, s8 + q + 1);
;         }
;         yw[s8 * 32] = ykeep;
;       }
;     } else {
;       const int pw = w - 4;
;       if (ch > 0) flush(ch - 1, buf ^ 1, tid - 256);
;       if (ch + 1 < 136) produce(ch + 1, buf ^ 1, pw, 4);
;     }
;     __syncthreads();
;   }
	ds_read_b128 v[48:51], v117 offset:47616
	ds_read_b128 v[52:55], v117 offset:47632
	ds_read_b128 v[56:59], v117 offset:47872
	ds_read_b128 v[60:63], v117 offset:47888
	ds_read_b128 v[64:67], v117 offset:48128
	ds_read_b128 v[68:71], v117 offset:48144
	ds_read_b128 v[72:75], v117 offset:48384
	ds_read_b128 v[76:79], v117 offset:48400
	ds_read_b128 v[80:83], v117 offset:48640
	ds_read_b128 v[84:87], v117 offset:48656
	v_pk_mul_f32 v[92:93], v[0:1], v[8:9]
	v_pk_mul_f32 v[94:95], v[2:3], v[10:11]
	v_pk_fma_f32 v[92:93], v[4:5], v[12:13], v[92:93]
	v_pk_fma_f32 v[94:95], v[6:7], v[14:15], v[94:95]
	v_add_f32_dpp v114, v114, v114 quad_perm:[1,0,3,2] row_mask:0xf bank_mask:0xf bound_ctrl:1
	v_pk_add_f32 v[92:93], v[92:93], v[94:95]
	v_pk_mul_f32 v[102:103], v[32:33], v[90:91] op_sel_hi:[1,0]
	v_add_f32_dpp v114, v114, v114 quad_perm:[2,3,0,1] row_mask:0xf bank_mask:0xf bound_ctrl:1
	v_add_f32_e32 v110, v92, v93
	v_pk_mul_f32 v[104:105], v[34:35], v[90:91] op_sel_hi:[1,0]
	v_add_f32_dpp v115, v114, v114 row_half_mirror row_mask:0xf bank_mask:0xf bound_ctrl:1
	v_pk_mul_f32 v[106:107], v[36:37], v[90:91] op_sel_hi:[1,0]
	v_add_f32_dpp v110, v110, v110 quad_perm:[1,0,3,2] row_mask:0xf bank_mask:0xf bound_ctrl:1
	v_pk_mul_f32 v[108:109], v[38:39], v[90:91] op_sel_hi:[1,0]
	v_pk_fma_f32 v[0:1], v[0:1], v[16:17], v[102:103]
	v_add_f32_dpp v110, v110, v110 quad_perm:[2,3,0,1] row_mask:0xf bank_mask:0xf bound_ctrl:1
	v_pk_fma_f32 v[2:3], v[2:3], v[18:19], v[104:105]
	v_pk_fma_f32 v[4:5], v[4:5], v[20:21], v[106:107]
	v_add_f32_dpp v112, v110, v110 row_half_mirror row_mask:0xf bank_mask:0xf bound_ctrl:1
	v_pk_fma_f32 v[6:7], v[6:7], v[22:23], v[108:109]
	v_cndmask_b32_e64 v116, v116, v115, s[0:1]
	v_pk_fma_f32 v[0:1], v[24:25], v[112:113], v[0:1] op_sel_hi:[1,0,1]
	v_pk_fma_f32 v[2:3], v[26:27], v[112:113], v[2:3] op_sel_hi:[1,0,1]
	v_pk_fma_f32 v[4:5], v[28:29], v[112:113], v[4:5] op_sel_hi:[1,0,1]
	v_pk_fma_f32 v[6:7], v[30:31], v[112:113], v[6:7] op_sel_hi:[1,0,1]
	v_pk_mul_f32 v[98:99], v[0:1], v[40:41]
	v_pk_mul_f32 v[100:101], v[2:3], v[42:43]
	v_pk_fma_f32 v[98:99], v[4:5], v[44:45], v[98:99]
	v_pk_fma_f32 v[100:101], v[6:7], v[46:47], v[100:101]
	v_pk_add_f32 v[98:99], v[98:99], v[100:101]
	v_add_f32_e32 v114, v98, v99
	s_waitcnt lgkmcnt(0)
	v_pk_mul_f32 v[92:93], v[0:1], v[48:49]
	v_pk_mul_f32 v[94:95], v[2:3], v[50:51]
	v_pk_fma_f32 v[92:93], v[4:5], v[52:53], v[92:93]
	v_pk_fma_f32 v[94:95], v[6:7], v[54:55], v[94:95]
	v_add_f32_dpp v114, v114, v114 quad_perm:[1,0,3,2] row_mask:0xf bank_mask:0xf bound_ctrl:1
	v_pk_add_f32 v[92:93], v[92:93], v[94:95]
	v_pk_mul_f32 v[102:103], v[72:73], v[90:91] op_sel:[0,1] op_sel_hi:[1,1]
	v_add_f32_dpp v114, v114, v114 quad_perm:[2,3,0,1] row_mask:0xf bank_mask:0xf bound_ctrl:1
	v_add_f32_e32 v110, v92, v93
	v_pk_mul_f32 v[104:105], v[74:75], v[90:91] op_sel:[0,1] op_sel_hi:[1,1]
	v_add_f32_dpp v115, v114, v114 row_half_mirror row_mask:0xf bank_mask:0xf bound_ctrl:1
	v_pk_mul_f32 v[106:107], v[76:77], v[90:91] op_sel:[0,1] op_sel_hi:[1,1]
	v_add_f32_dpp v110, v110, v110 quad_perm:[1,0,3,2] row_mask:0xf bank_mask:0xf bound_ctrl:1
	v_pk_mul_f32 v[108:109], v[78:79], v[90:91] op_sel:[0,1] op_sel_hi:[1,1]
	v_pk_fma_f32 v[0:1], v[0:1], v[56:57], v[102:103]
	v_add_f32_dpp v110, v110, v110 quad_perm:[2,3,0,1] row_mask:0xf bank_mask:0xf bound_ctrl:1
	v_pk_fma_f32 v[2:3], v[2:3], v[58:59], v[104:105]
	v_pk_fma_f32 v[4:5], v[4:5], v[60:61], v[106:107]
	v_add_f32_dpp v112, v110, v110 row_half_mirror row_mask:0xf bank_mask:0xf bound_ctrl:1
	v_pk_fma_f32 v[6:7], v[6:7], v[62:63], v[108:109]
	v_cndmask_b32_e64 v116, v116, v115, s[96:97]
	v_pk_fma_f32 v[0:1], v[64:65], v[112:113], v[0:1] op_sel_hi:[1,0,1]
	v_pk_fma_f32 v[2:3], v[66:67], v[112:113], v[2:3] op_sel_hi:[1,0,1]
	v_pk_fma_f32 v[4:5], v[68:69], v[112:113], v[4:5] op_sel_hi:[1,0,1]
	v_pk_fma_f32 v[6:7], v[70:71], v[112:113], v[6:7] op_sel_hi:[1,0,1]
	v_pk_mul_f32 v[98:99], v[0:1], v[80:81]
	v_pk_mul_f32 v[100:101], v[2:3], v[82:83]
	v_pk_fma_f32 v[98:99], v[4:5], v[84:85], v[98:99]
	v_pk_fma_f32 v[100:101], v[6:7], v[86:87], v[100:101]
	v_pk_add_f32 v[98:99], v[98:99], v[100:101]
	v_add_f32_e32 v114, v98, v99
	s_nop 1
	v_add_f32_dpp v114, v114, v114 quad_perm:[1,0,3,2] row_mask:0xf bank_mask:0xf bound_ctrl:1
	s_nop 1
	v_add_f32_dpp v114, v114, v114 quad_perm:[2,3,0,1] row_mask:0xf bank_mask:0xf bound_ctrl:1
	s_nop 1
	v_add_f32_dpp v115, v114, v114 row_half_mirror row_mask:0xf bank_mask:0xf bound_ctrl:1
	v_mov_b32_e32 v114, 0
	v_cndmask_b32_e64 v116, v116, v115, vcc
	ds_write_b32 v119, v116 offset:3072
	v_xor_b32_e32 v117, 0xc000, v117
	v_xor_b32_e32 v118, 0xc000, v118
	v_xor_b32_e32 v119, 0x1000, v119
	s_add_u32 s46, s46, 1
	s_cmp_lt_u32 s46, 136
	s_waitcnt lgkmcnt(0)
	s_barrier
	s_cbranch_scc1 .Lsc_cloop
	s_branch .LBB0_192

; __global__ void __launch_bounds__(512) fwd_megakernel(Params p, int ph_lo, int ph_hi) {
;   extern __shared__ __attribute__((aligned(16))) char smem[];
	.amdhsa_kernel _Z14fwd_megakernel6Paramsii
		.amdhsa_group_segment_fixed_size 0
		.amdhsa_private_segment_fixed_size 0
		.amdhsa_kernarg_size 568
		.amdhsa_user_sgpr_count 2
		.amdhsa_user_sgpr_dispatch_ptr 0
		.amdhsa_user_sgpr_queue_ptr 0
		.amdhsa_user_sgpr_kernarg_segment_ptr 1
		.amdhsa_user_sgpr_dispatch_id 0
		.amdhsa_user_sgpr_kernarg_preload_length 0
		.amdhsa_user_sgpr_kernarg_preload_offset 0
		.amdhsa_user_sgpr_private_segment_size 0
		.amdhsa_uses_dynamic_stack 0
		.amdhsa_enable_private_segment 0
		.amdhsa_system_sgpr_workgroup_id_x 1
		.amdhsa_system_sgpr_workgroup_id_y 0
		.amdhsa_system_sgpr_workgroup_id_z 0
		.amdhsa_system_sgpr_workgroup_info 0
		.amdhsa_system_vgpr_workitem_id 2
		.amdhsa_next_free_vgpr 256
		.amdhsa_next_free_sgpr 102
		.amdhsa_accum_offset 256
		.amdhsa_reserve_vcc 1
		.amdhsa_float_round_mode_32 0
		.amdhsa_float_round_mode_16_64 0
		.amdhsa_float_denorm_mode_32 3
		.amdhsa_float_denorm_mode_16_64 3
		.amdhsa_dx10_clamp 1
		.amdhsa_ieee_mode 1
		.amdhsa_fp16_overflow 0
		.amdhsa_tg_split 0
		.amdhsa_exception_fp_ieee_invalid_op 0
		.amdhsa_exception_fp_denorm_src 0
		.amdhsa_exception_fp_ieee_div_zero 0
		.amdhsa_exception_fp_ieee_overflow 0
		.amdhsa_exception_fp_ieee_underflow 0
		.amdhsa_exception_fp_ieee_inexact 0
		.amdhsa_exception_int_div_zero 0
	.end_amdhsa_kernel

; __global__ void __launch_bounds__(512) fwd_megakernel(Params p, int ph_lo, int ph_hi) {
;   extern __shared__ __attribute__((aligned(16))) char smem[];
amdhsa.kernels:
  - .agpr_count:     0
    .args:
      - .offset:         0
        .size:           304
        .value_kind:     by_value
      - .offset:         304
        .size:           4
        .value_kind:     by_value
      - .offset:         308
        .size:           4
        .value_kind:     by_value
      - .offset:         312
        .size:           4
        .value_kind:     hidden_block_count_x
      - .offset:         316
        .size:           4
        .value_kind:     hidden_block_count_y
      - .offset:         320
        .size:           4
        .value_kind:     hidden_block_count_z
      - .offset:         324
        .size:           2
        .value_kind:     hidden_group_size_x
      - .offset:         326
        .size:           2
        .value_kind:     hidden_group_size_y
      - .offset:         328
        .size:           2
        .value_kind:     hidden_group_size_z
      - .offset:         330
        .size:           2
        .value_kind:     hidden_remainder_x
      - .offset:         332
        .size:           2
        .value_kind:     hidden_remainder_y
      - .offset:         334
        .size:           2
        .value_kind:     hidden_remainder_z
      - .offset:         352
        .size:           8
        .value_kind:     hidden_global_offset_x
      - .offset:         360
        .size:           8
        .value_kind:     hidden_global_offset_y
      - .offset:         368
        .size:           8
        .value_kind:     hidden_global_offset_z
      - .offset:         376
        .size:           2
        .value_kind:     hidden_grid_dims
      - .offset:         400
        .size:           8
        .value_kind:     hidden_multigrid_sync_arg
      - .offset:         432
        .size:           4
        .value_kind:     hidden_dynamic_lds_size
    .group_segment_fixed_size: 0
    .kernarg_segment_align: 8
    .kernarg_segment_size: 568
    .language:       OpenCL C
    .language_version:
      - 2
      - 0
    .max_flat_workgroup_size: 512
    .name:           _Z14fwd_megakernel6Paramsii
    .private_segment_fixed_size: 0
    .sgpr_count:     108
    .sgpr_spill_count: 319
    .symbol:         _Z14fwd_megakernel6Paramsii.kd
    .uniform_work_group_size: 1
    .uses_dynamic_stack: false
    .vgpr_count:     256
    .vgpr_spill_count: 0
    .wavefront_size: 64
